# gemm8: first k-tile iteration peeled with C=0 MFMAs, the 128-register accumulator zeroing deleted
# baseline (speedup 1.0000x reference)
; #define MFMA16(a, b, c) __builtin_amdgcn_mfma_f32_16x16x32_bf16((a), (b), (c), 0, 0, 0)
; #define G8_STAGE(buf_, ap_, bp_) G8_STAGE_R(buf_, ap_, bp_, 0, 4)
; template <class Epi>
; DI void gemm8_tile(const bf16_t* __restrict__ Ab, int lda, const bf16_t* __restrict__ Bb, int ldb, int K, int brow, int bcol, const Epi epi,
;                    bool staged, bool has_next, const bf16_t* __restrict__ Abn, const bf16_t* __restrict__ Bbn) {
;     ...
;   for (int i = 0; i < 4; ++i) { int R, C; stage_rc2(wid * 1024 + i * 8192 + lane * 16, R, C); aoff[i] = (unsigned)R * (unsigned)lda + (unsigned)C; boff[i] = (unsigned)R * (unsigned)ldb + (unsigned)C; }
;     ...
;   f32x4 acc[8][4];
; #pragma unroll
;   for (int m = 0; m < 8; ++m)
; #pragma unroll
;     for (int n = 0; n < 4; ++n) acc[m][n] = (f32x4){0.f, 0.f, 0.f, 0.f};
;   const int nt = K / 64;
;   if (!staged) {
;     G8_STAGE(0, Ab, Bb);
;     asm volatile("s_waitcnt vmcnt(0)" ::: "memory");
;     __syncthreads();
;   }
;   for (int t = 0; t < nt; ++t) {
;     const int cur = t & 1;
;     const unsigned char* sa = smem + cur * G8_STAGE_B;
;     const unsigned char* sb = sa + G8_TILE_B;
; #pragma unroll
;     for (int ks = 0; ks < 2; ++ks) {
;       bf16x8 At[8], Bf[4];
;       Bf[0] = *(const bf16x8*)(sb + lds_byte2(wc * 64 + fr, ks * 32 + fq * 8));
;       At[0] = *(const bf16x8*)(sa + lds_byte2(wr * 128 + fr, ks * 32 + fq * 8));
; #pragma unroll
;       for (int n = 1; n < 4; ++n) Bf[n] = *(const bf16x8*)(sb + lds_byte2(wc * 64 + n * 16 + fr, ks * 32 + fq * 8));
; #pragma unroll
;       for (int m = 1; m < 8; ++m) At[m] = *(const bf16x8*)(sa + lds_byte2(wr * 128 + m * 16 + fr, ks * 32 + fq * 8));
;       {
;         __builtin_amdgcn_sched_barrier(0);
;         if (t + 1 < nt) { G8_STAGE_R(cur ^ 1, Ab + (t + 1) * 64, Bb + (t + 1) * 64, 2 * ks, 2 * ks + 2); }
;         else if (has_next) { G8_STAGE_R(0, Abn, Bbn, 2 * ks, 2 * ks + 2); }
;         __builtin_amdgcn_sched_barrier(0);
;       }
; #pragma unroll
;       for (int m = 0; m < 8; ++m)
; #pragma unroll
;         for (int n = 0; n < 4; ++n) acc[m][n] = MFMA16(At[m], Bf[n], acc[m][n]);
.LBB0_461:
	v_readlane_b32 s0, v253, 4
	s_add_u32 s0, s0, s71
	v_readlane_b32 s1, v253, 5
	v_lshlrev_b64 v[212:213], 1, v[0:1]
	s_addc_u32 s1, s1, s78
	v_lshlrev_b64 v[214:215], 1, v[6:7]
	v_lshlrev_b64 v[146:147], 1, v[4:5]
	v_lshlrev_b64 v[148:149], 1, v[2:3]
	v_lshl_add_u64 v[130:131], s[0:1], 0, v[212:213]
	v_lshl_add_u64 v[132:133], s[0:1], 0, v[214:215]
	v_lshl_add_u64 v[134:135], s[0:1], 0, v[146:147]
	v_lshl_add_u64 v[136:137], s[0:1], 0, v[148:149]
	s_lshl_b32 s0, s59, 3
	s_add_i32 s0, s28, s0
	s_add_i32 s0, s0, s70
	s_lshl_b32 s1, s58, 3
	s_sub_i32 s0, s0, s1
	s_lshl_b32 s1, s0, 8
	s_mul_i32 s0, s0, 0x88000
	v_readlane_b32 s8, v253, 6
	v_and_b32_e32 v228, 63, v8
	v_and_b32_e32 v229, 3, v9
	v_ashrrev_i32_e32 v9, 8, v8
	v_and_b32_e32 v223, 15, v8
	v_and_b32_e32 v10, 48, v8
	v_lshlrev_b32_e32 v12, 2, v8
	v_lshlrev_b32_e32 v8, 6, v8
	s_mul_hi_i32 s1, s1, 0x880
	s_add_u32 s0, s8, s0
	v_readlane_b32 s8, v253, 7
	v_lshlrev_b32_e32 v11, 6, v223
	v_and_b32_e32 v12, 32, v12
	v_lshlrev_b32_e32 v153, 14, v9
	v_and_b32_e32 v8, 0x3c0, v8
	s_addc_u32 s1, s8, s1
	v_lshlrev_b32_e32 v151, 13, v229
	v_bitop3_b32 v152, v11, v12, v10 bitop3:0x36
	v_lshlrev_b32_e32 v230, 7, v9
	v_or_b32_e32 v150, 0x800, v153
	v_bitop3_b32 v158, v8, v12, v10 bitop3:0x36
	v_or_b32_e32 v167, 0x1000, v153
	v_or_b32_e32 v166, 0x1800, v153
	v_or_b32_e32 v165, 0x2000, v153
	v_or_b32_e32 v164, 0x2800, v153
	v_or_b32_e32 v163, 0x3000, v153
	v_or_b32_e32 v162, 0x3800, v153
	v_lshl_add_u64 v[138:139], s[0:1], 0, v[212:213]
	v_lshl_add_u64 v[140:141], s[0:1], 0, v[214:215]
	v_lshl_add_u64 v[142:143], s[0:1], 0, v[146:147]
	v_lshl_add_u64 v[144:145], s[0:1], 0, v[148:149]
	s_mov_b64 s[0:1], 0
	s_mov_b32 s14, 0
	s_waitcnt vmcnt(8)
	s_mov_b32 s56, 0
	v_add3_u32 v0, s56, v152, v151
	v_add3_u32 v159, s56, v152, v153
	v_add3_u32 v209, s56, v158, v167
	v_add3_u32 v240, s56, v158, v165
	v_add3_u32 v242, s56, v158, v163
	v_add3_u32 v208, s56, v158, v150
	v_add3_u32 v231, s56, v158, v166
	v_add3_u32 v241, s56, v158, v164
	v_add3_u32 v243, s56, v158, v162
	ds_read_b128 v[168:171], v0 offset:32768
	ds_read_b128 v[172:175], v0 offset:34816
	ds_read_b128 v[184:187], v159
	ds_read_b128 v[188:191], v208
	ds_read_b128 v[192:195], v209
	ds_read_b128 v[196:199], v231
	ds_read_b128 v[200:203], v240
	ds_read_b128 v[204:207], v241
	ds_read_b128 v[232:235], v242
	ds_read_b128 v[236:239], v243
	ds_read_b128 v[176:179], v0 offset:36864
	ds_read_b128 v[180:183], v0 offset:38912
	s_and_b32 s15, s14, 0x10000
	s_xor_b32 s56, s15, 0x10000
	v_add_u32_e32 v244, s56, v157
	s_nop 0
	v_readfirstlane_b32 s15, v244
	s_waitcnt lgkmcnt(8)
	v_mfma_f32_16x16x32_bf16 v[126:129], v[184:187], v[168:171], 0
	v_mfma_f32_16x16x32_bf16 v[122:125], v[184:187], v[172:175], 0
	s_mov_b32 m0, s15
	v_lshl_add_u64 v[160:161], v[144:145], 0, s[0:1]
	global_load_lds_dwordx4 v[160:161], off
	v_mfma_f32_16x16x32_bf16 v[110:113], v[188:191], v[168:171], 0
	v_mfma_f32_16x16x32_bf16 v[106:109], v[188:191], v[172:175], 0
	s_add_u32 m0, s15, 0x8000
	v_lshl_add_u64 v[160:161], v[136:137], 0, s[0:1]
	global_load_lds_dwordx4 v[160:161], off
	s_waitcnt lgkmcnt(6)
	v_mfma_f32_16x16x32_bf16 v[94:97], v[192:195], v[168:171], 0
	v_mfma_f32_16x16x32_bf16 v[90:93], v[192:195], v[172:175], 0
	s_add_u32 m0, s15, 0x2000
	v_lshl_add_u64 v[160:161], v[142:143], 0, s[0:1]
	global_load_lds_dwordx4 v[160:161], off
	v_mfma_f32_16x16x32_bf16 v[78:81], v[196:199], v[168:171], 0
	v_mfma_f32_16x16x32_bf16 v[74:77], v[196:199], v[172:175], 0
	s_add_u32 m0, s15, 0xa000
	v_lshl_add_u64 v[160:161], v[134:135], 0, s[0:1]
	global_load_lds_dwordx4 v[160:161], off
	s_waitcnt lgkmcnt(4)
	v_mfma_f32_16x16x32_bf16 v[62:65], v[200:203], v[168:171], 0
	v_mfma_f32_16x16x32_bf16 v[58:61], v[200:203], v[172:175], 0
	s_add_u32 m0, s15, 0x4000
	v_lshl_add_u64 v[160:161], v[140:141], 0, s[0:1]
	global_load_lds_dwordx4 v[160:161], off
	v_mfma_f32_16x16x32_bf16 v[46:49], v[204:207], v[168:171], 0
	v_mfma_f32_16x16x32_bf16 v[42:45], v[204:207], v[172:175], 0
	s_add_u32 m0, s15, 0xc000
	v_lshl_add_u64 v[160:161], v[132:133], 0, s[0:1]
	global_load_lds_dwordx4 v[160:161], off
	s_waitcnt lgkmcnt(2)
	v_mfma_f32_16x16x32_bf16 v[30:33], v[232:235], v[168:171], 0
	v_mfma_f32_16x16x32_bf16 v[26:29], v[232:235], v[172:175], 0
	s_add_u32 m0, s15, 0x6000
	v_lshl_add_u64 v[160:161], v[138:139], 0, s[0:1]
	global_load_lds_dwordx4 v[160:161], off
	v_mfma_f32_16x16x32_bf16 v[14:17], v[236:239], v[168:171], 0
	v_mfma_f32_16x16x32_bf16 v[10:13], v[236:239], v[172:175], 0
	s_add_u32 m0, s15, 0xe000
	v_lshl_add_u64 v[160:161], v[130:131], 0, s[0:1]
	global_load_lds_dwordx4 v[160:161], off
	ds_read_b128 v[168:171], v0 offset:33792
	ds_read_b128 v[172:175], v0 offset:35840
	s_waitcnt lgkmcnt(2)
; #define MFMA16(a, b, c) __builtin_amdgcn_mfma_f32_16x16x32_bf16((a), (b), (c), 0, 0, 0)
; template <class Epi>
; DI void gemm8_tile(const bf16_t* __restrict__ Ab, int lda, const bf16_t* __restrict__ Bb, int ldb, int K, int brow, int bcol, const Epi epi,
;                    bool staged, bool has_next, const bf16_t* __restrict__ Abn, const bf16_t* __restrict__ Bbn) {
;     ...
; #pragma unroll
;     for (int ks = 0; ks < 2; ++ks) {
;       bf16x8 At[8], Bf[4];
;       Bf[0] = *(const bf16x8*)(sb + lds_byte2(wc * 64 + fr, ks * 32 + fq * 8));
;       At[0] = *(const bf16x8*)(sa + lds_byte2(wr * 128 + fr, ks * 32 + fq * 8));
; #pragma unroll
;       for (int n = 1; n < 4; ++n) Bf[n] = *(const bf16x8*)(sb + lds_byte2(wc * 64 + n * 16 + fr, ks * 32 + fq * 8));
; #pragma unroll
;       for (int m = 1; m < 8; ++m) At[m] = *(const bf16x8*)(sa + lds_byte2(wr * 128 + m * 16 + fr, ks * 32 + fq * 8));
;       {
;         __builtin_amdgcn_sched_barrier(0);
;         if (t + 1 < nt) { G8_STAGE_R(cur ^ 1, Ab + (t + 1) * 64, Bb + (t + 1) * 64, 2 * ks, 2 * ks + 2); }
;         else if (has_next) { G8_STAGE_R(0, Abn, Bbn, 2 * ks, 2 * ks + 2); }
;         __builtin_amdgcn_sched_barrier(0);
;       }
; #pragma unroll
;       for (int m = 0; m < 8; ++m)
; #pragma unroll
;         for (int n = 0; n < 4; ++n) acc[m][n] = MFMA16(At[m], Bf[n], acc[m][n]);
;       __builtin_amdgcn_sched_barrier(0);
;     }
;     asm volatile("s_waitcnt vmcnt(0)" ::: "memory");
;     __syncthreads();
	v_mfma_f32_16x16x32_bf16 v[118:121], v[184:187], v[176:179], 0
	v_mfma_f32_16x16x32_bf16 v[114:117], v[184:187], v[180:183], 0
	ds_read_b128 v[184:187], v159 offset:1024
	v_mfma_f32_16x16x32_bf16 v[102:105], v[188:191], v[176:179], 0
	v_mfma_f32_16x16x32_bf16 v[98:101], v[188:191], v[180:183], 0
	ds_read_b128 v[188:191], v208 offset:1024
	v_mfma_f32_16x16x32_bf16 v[86:89], v[192:195], v[176:179], 0
	v_mfma_f32_16x16x32_bf16 v[82:85], v[192:195], v[180:183], 0
	ds_read_b128 v[192:195], v209 offset:1024
	v_mfma_f32_16x16x32_bf16 v[70:73], v[196:199], v[176:179], 0
	v_mfma_f32_16x16x32_bf16 v[66:69], v[196:199], v[180:183], 0
	ds_read_b128 v[196:199], v231 offset:1024
	v_mfma_f32_16x16x32_bf16 v[54:57], v[200:203], v[176:179], 0
	v_mfma_f32_16x16x32_bf16 v[50:53], v[200:203], v[180:183], 0
	ds_read_b128 v[200:203], v240 offset:1024
	v_mfma_f32_16x16x32_bf16 v[38:41], v[204:207], v[176:179], 0
	v_mfma_f32_16x16x32_bf16 v[34:37], v[204:207], v[180:183], 0
	ds_read_b128 v[204:207], v241 offset:1024
	v_mfma_f32_16x16x32_bf16 v[22:25], v[232:235], v[176:179], 0
	v_mfma_f32_16x16x32_bf16 v[18:21], v[232:235], v[180:183], 0
	ds_read_b128 v[232:235], v242 offset:1024
	v_mfma_f32_16x16x32_bf16 v[6:9], v[236:239], v[176:179], 0
	v_mfma_f32_16x16x32_bf16 v[2:5], v[236:239], v[180:183], 0
	ds_read_b128 v[236:239], v243 offset:1024
	ds_read_b128 v[176:179], v0 offset:37888
	ds_read_b128 v[180:183], v0 offset:39936
	s_waitcnt lgkmcnt(8)
	v_mfma_f32_16x16x32_bf16 v[126:129], v[184:187], v[168:171], v[126:129]
	v_mfma_f32_16x16x32_bf16 v[122:125], v[184:187], v[172:175], v[122:125]
	v_add3_u32 v0, s56, v152, v151
	v_mfma_f32_16x16x32_bf16 v[110:113], v[188:191], v[168:171], v[110:113]
	v_mfma_f32_16x16x32_bf16 v[106:109], v[188:191], v[172:175], v[106:109]
	v_add3_u32 v159, s56, v152, v153
	s_waitcnt lgkmcnt(6)
	v_mfma_f32_16x16x32_bf16 v[94:97], v[192:195], v[168:171], v[94:97]
	v_mfma_f32_16x16x32_bf16 v[90:93], v[192:195], v[172:175], v[90:93]
	v_add3_u32 v209, s56, v158, v167
	v_mfma_f32_16x16x32_bf16 v[78:81], v[196:199], v[168:171], v[78:81]
	v_mfma_f32_16x16x32_bf16 v[74:77], v[196:199], v[172:175], v[74:77]
	v_add3_u32 v240, s56, v158, v165
	s_waitcnt lgkmcnt(4)
	v_mfma_f32_16x16x32_bf16 v[62:65], v[200:203], v[168:171], v[62:65]
	v_mfma_f32_16x16x32_bf16 v[58:61], v[200:203], v[172:175], v[58:61]
	v_add3_u32 v242, s56, v158, v163
	v_mfma_f32_16x16x32_bf16 v[46:49], v[204:207], v[168:171], v[46:49]
	v_mfma_f32_16x16x32_bf16 v[42:45], v[204:207], v[172:175], v[42:45]
	v_add3_u32 v208, s56, v158, v150
	s_waitcnt lgkmcnt(2)
	v_mfma_f32_16x16x32_bf16 v[30:33], v[232:235], v[168:171], v[30:33]
	v_mfma_f32_16x16x32_bf16 v[26:29], v[232:235], v[172:175], v[26:29]
	v_add3_u32 v231, s56, v158, v166
	v_mfma_f32_16x16x32_bf16 v[14:17], v[236:239], v[168:171], v[14:17]
	v_mfma_f32_16x16x32_bf16 v[10:13], v[236:239], v[172:175], v[10:13]
	v_add3_u32 v241, s56, v158, v164
	v_add3_u32 v243, s56, v158, v162
	s_waitcnt vmcnt(0) lgkmcnt(0)
	s_barrier
	ds_read_b128 v[168:171], v0 offset:32768
	ds_read_b128 v[172:175], v0 offset:34816
	v_mfma_f32_16x16x32_bf16 v[118:121], v[184:187], v[176:179], v[118:121]
	v_mfma_f32_16x16x32_bf16 v[114:117], v[184:187], v[180:183], v[114:117]
	ds_read_b128 v[184:187], v159
	v_mfma_f32_16x16x32_bf16 v[102:105], v[188:191], v[176:179], v[102:105]
	v_mfma_f32_16x16x32_bf16 v[98:101], v[188:191], v[180:183], v[98:101]
	ds_read_b128 v[188:191], v208
	v_mfma_f32_16x16x32_bf16 v[86:89], v[192:195], v[176:179], v[86:89]
	v_mfma_f32_16x16x32_bf16 v[82:85], v[192:195], v[180:183], v[82:85]
	ds_read_b128 v[192:195], v209
	v_mfma_f32_16x16x32_bf16 v[70:73], v[196:199], v[176:179], v[70:73]
	v_mfma_f32_16x16x32_bf16 v[66:69], v[196:199], v[180:183], v[66:69]
	ds_read_b128 v[196:199], v231
	v_mfma_f32_16x16x32_bf16 v[54:57], v[200:203], v[176:179], v[54:57]
	v_mfma_f32_16x16x32_bf16 v[50:53], v[200:203], v[180:183], v[50:53]
	ds_read_b128 v[200:203], v240
	v_mfma_f32_16x16x32_bf16 v[38:41], v[204:207], v[176:179], v[38:41]
	v_mfma_f32_16x16x32_bf16 v[34:37], v[204:207], v[180:183], v[34:37]
	ds_read_b128 v[204:207], v241
	v_mfma_f32_16x16x32_bf16 v[22:25], v[232:235], v[176:179], v[22:25]
	v_mfma_f32_16x16x32_bf16 v[18:21], v[232:235], v[180:183], v[18:21]
	ds_read_b128 v[232:235], v242
	v_mfma_f32_16x16x32_bf16 v[6:9], v[236:239], v[176:179], v[6:9]
	v_mfma_f32_16x16x32_bf16 v[2:5], v[236:239], v[180:183], v[2:5]
	ds_read_b128 v[236:239], v243
	ds_read_b128 v[176:179], v0 offset:36864
	ds_read_b128 v[180:183], v0 offset:38912
	s_add_u32 s0, s0, 0x80
	s_addc_u32 s1, s1, 0
	s_add_i32 s14, s14, 0x10000

; #define MFMA16(a, b, c) __builtin_amdgcn_mfma_f32_16x16x32_bf16((a), (b), (c), 0, 0, 0)
; #define G8_STAGE(buf_, ap_, bp_) G8_STAGE_R(buf_, ap_, bp_, 0, 4)
; template <class Epi>
; DI void gemm8_tile(const bf16_t* __restrict__ Ab, int lda, const bf16_t* __restrict__ Bb, int ldb, int K, int brow, int bcol, const Epi epi,
;                    bool staged, bool has_next, const bf16_t* __restrict__ Abn, const bf16_t* __restrict__ Bbn) {
;     ...
;   for (int i = 0; i < 4; ++i) { int R, C; stage_rc2(wid * 1024 + i * 8192 + lane * 16, R, C); aoff[i] = (unsigned)R * (unsigned)lda + (unsigned)C; boff[i] = (unsigned)R * (unsigned)ldb + (unsigned)C; }
;     ...
;   f32x4 acc[8][4];
; #pragma unroll
;   for (int m = 0; m < 8; ++m)
; #pragma unroll
;     for (int n = 0; n < 4; ++n) acc[m][n] = (f32x4){0.f, 0.f, 0.f, 0.f};
;   const int nt = K / 64;
;   if (!staged) {
;     G8_STAGE(0, Ab, Bb);
;     asm volatile("s_waitcnt vmcnt(0)" ::: "memory");
;     __syncthreads();
;   }
;   for (int t = 0; t < nt; ++t) {
;     const int cur = t & 1;
;     const unsigned char* sa = smem + cur * G8_STAGE_B;
;     const unsigned char* sb = sa + G8_TILE_B;
; #pragma unroll
;     for (int ks = 0; ks < 2; ++ks) {
;       bf16x8 At[8], Bf[4];
;       Bf[0] = *(const bf16x8*)(sb + lds_byte2(wc * 64 + fr, ks * 32 + fq * 8));
;       At[0] = *(const bf16x8*)(sa + lds_byte2(wr * 128 + fr, ks * 32 + fq * 8));
; #pragma unroll
;       for (int n = 1; n < 4; ++n) Bf[n] = *(const bf16x8*)(sb + lds_byte2(wc * 64 + n * 16 + fr, ks * 32 + fq * 8));
; #pragma unroll
;       for (int m = 1; m < 8; ++m) At[m] = *(const bf16x8*)(sa + lds_byte2(wr * 128 + m * 16 + fr, ks * 32 + fq * 8));
;       {
;         __builtin_amdgcn_sched_barrier(0);
;         if (t + 1 < nt) { G8_STAGE_R(cur ^ 1, Ab + (t + 1) * 64, Bb + (t + 1) * 64, 2 * ks, 2 * ks + 2); }
;         else if (has_next) { G8_STAGE_R(0, Abn, Bbn, 2 * ks, 2 * ks + 2); }
;         __builtin_amdgcn_sched_barrier(0);
;       }
; #pragma unroll
;       for (int m = 0; m < 8; ++m)
; #pragma unroll
;         for (int n = 0; n < 4; ++n) acc[m][n] = MFMA16(At[m], Bf[n], acc[m][n]);
.LBB0_482:
	s_lshl_b32 s0, s71, 3
	s_add_i32 s0, s28, s0
	s_add_i32 s0, s0, s75
	s_lshl_b32 s1, s70, 3
	s_sub_i32 s0, s0, s1
	s_lshl_b32 s1, s0, 8
	s_mul_i32 s0, s0, 0x168000
	s_mul_hi_i32 s1, s1, 0x1680
	s_add_u32 s0, s91, s0
	v_lshlrev_b64 v[178:179], 1, v[4:5]
	s_addc_u32 s1, s72, s1
	v_lshlrev_b64 v[180:181], 1, v[2:3]
	v_lshlrev_b64 v[194:195], 1, v[6:7]
	v_lshlrev_b64 v[196:197], 1, v[0:1]
	v_and_b32_e32 v198, 15, v8
	v_lshl_add_u64 v[130:131], s[0:1], 0, v[178:179]
	v_lshl_add_u64 v[132:133], s[0:1], 0, v[180:181]
	v_lshl_add_u64 v[134:135], s[0:1], 0, v[194:195]
	v_lshl_add_u64 v[136:137], s[0:1], 0, v[196:197]
	v_readlane_b32 s0, v253, 8
	v_and_b32_e32 v206, 63, v8
	v_ashrrev_i32_e32 v10, 8, v8
	v_and_b32_e32 v204, 3, v9
	v_and_b32_e32 v9, 48, v8
	v_lshlrev_b32_e32 v199, 2, v198
	v_lshlrev_b32_e32 v8, 6, v8
	s_add_u32 s0, s0, s78
	v_readlane_b32 s1, v253, 9
	v_lshlrev_b32_e32 v11, 6, v198
	v_and_b32_e32 v12, 32, v199
	v_lshlrev_b32_e32 v156, 14, v10
	v_and_b32_e32 v8, 0x3c0, v8
	s_addc_u32 s1, s1, s79
	v_lshlrev_b32_e32 v153, 13, v204
	v_bitop3_b32 v155, v11, v12, v9 bitop3:0x36
	v_lshlrev_b32_e32 v205, 7, v10
	v_or_b32_e32 v150, 0x800, v156
	v_bitop3_b32 v154, v8, v12, v9 bitop3:0x36
	v_or_b32_e32 v152, 0x1000, v156
	v_or_b32_e32 v151, 0x1800, v156
	v_or_b32_e32 v149, 0x2000, v156
	v_or_b32_e32 v148, 0x2800, v156
	v_or_b32_e32 v147, 0x3000, v156
	v_or_b32_e32 v146, 0x3800, v156
	v_lshl_add_u64 v[138:139], s[0:1], 0, v[178:179]
	v_lshl_add_u64 v[140:141], s[0:1], 0, v[180:181]
	v_lshl_add_u64 v[142:143], s[0:1], 0, v[194:195]
	v_lshl_add_u64 v[144:145], s[0:1], 0, v[196:197]
	s_mov_b64 s[0:1], 0
	s_mov_b32 s56, 0
	s_waitcnt vmcnt(8)
	s_mov_b32 s58, 0
	v_add3_u32 v0, s58, v155, v153
	v_add3_u32 v157, s58, v155, v156
	v_add3_u32 v238, s58, v154, v152
	v_add3_u32 v240, s58, v154, v149
	v_add3_u32 v242, s58, v154, v147
	v_add3_u32 v207, s58, v154, v150
	v_add3_u32 v239, s58, v154, v151
	v_add3_u32 v241, s58, v154, v148
	v_add3_u32 v243, s58, v154, v146
	ds_read_b128 v[158:161], v0 offset:32768
	ds_read_b128 v[162:165], v0 offset:34816
	ds_read_b128 v[174:177], v157
	ds_read_b128 v[186:189], v207
	ds_read_b128 v[190:193], v238
	ds_read_b128 v[212:215], v239
	ds_read_b128 v[222:225], v240
	ds_read_b128 v[226:229], v241
	ds_read_b128 v[230:233], v242
	ds_read_b128 v[234:237], v243
	ds_read_b128 v[166:169], v0 offset:36864
	ds_read_b128 v[170:173], v0 offset:38912
	s_and_b32 s57, s56, 0x10000
	s_xor_b32 s58, s57, 0x10000
	v_add_u32_e32 v244, s58, v185
	s_nop 0
	v_readfirstlane_b32 s57, v244
	s_waitcnt lgkmcnt(8)
	v_mfma_f32_16x16x32_bf16 v[126:129], v[174:177], v[158:161], 0
	v_mfma_f32_16x16x32_bf16 v[122:125], v[174:177], v[162:165], 0
	s_mov_b32 m0, s57
	v_lshl_add_u64 v[208:209], v[130:131], 0, s[0:1]
	global_load_lds_dwordx4 v[208:209], off
	v_mfma_f32_16x16x32_bf16 v[110:113], v[186:189], v[158:161], 0
	v_mfma_f32_16x16x32_bf16 v[106:109], v[186:189], v[162:165], 0
	s_add_u32 m0, s57, 0x8000
	v_lshl_add_u64 v[208:209], v[138:139], 0, s[0:1]
	global_load_lds_dwordx4 v[208:209], off
	s_waitcnt lgkmcnt(6)
	v_mfma_f32_16x16x32_bf16 v[94:97], v[190:193], v[158:161], 0
	v_mfma_f32_16x16x32_bf16 v[90:93], v[190:193], v[162:165], 0
	s_add_u32 m0, s57, 0x2000
	v_lshl_add_u64 v[208:209], v[132:133], 0, s[0:1]
	global_load_lds_dwordx4 v[208:209], off
	v_mfma_f32_16x16x32_bf16 v[78:81], v[212:215], v[158:161], 0
	v_mfma_f32_16x16x32_bf16 v[74:77], v[212:215], v[162:165], 0
	s_add_u32 m0, s57, 0xa000
	v_lshl_add_u64 v[208:209], v[140:141], 0, s[0:1]
	global_load_lds_dwordx4 v[208:209], off
	s_waitcnt lgkmcnt(4)
	v_mfma_f32_16x16x32_bf16 v[62:65], v[222:225], v[158:161], 0
	v_mfma_f32_16x16x32_bf16 v[58:61], v[222:225], v[162:165], 0
	s_add_u32 m0, s57, 0x4000
	v_lshl_add_u64 v[208:209], v[134:135], 0, s[0:1]
	global_load_lds_dwordx4 v[208:209], off
	v_mfma_f32_16x16x32_bf16 v[46:49], v[226:229], v[158:161], 0
	v_mfma_f32_16x16x32_bf16 v[42:45], v[226:229], v[162:165], 0
	s_add_u32 m0, s57, 0xc000
	v_lshl_add_u64 v[208:209], v[142:143], 0, s[0:1]
	global_load_lds_dwordx4 v[208:209], off
	s_waitcnt lgkmcnt(2)
	v_mfma_f32_16x16x32_bf16 v[30:33], v[230:233], v[158:161], 0
	v_mfma_f32_16x16x32_bf16 v[26:29], v[230:233], v[162:165], 0
	s_add_u32 m0, s57, 0x6000
	v_lshl_add_u64 v[208:209], v[136:137], 0, s[0:1]
	global_load_lds_dwordx4 v[208:209], off
	v_mfma_f32_16x16x32_bf16 v[14:17], v[234:237], v[158:161], 0
	v_mfma_f32_16x16x32_bf16 v[10:13], v[234:237], v[162:165], 0
	s_add_u32 m0, s57, 0xe000
	v_lshl_add_u64 v[208:209], v[144:145], 0, s[0:1]
	global_load_lds_dwordx4 v[208:209], off
	ds_read_b128 v[158:161], v0 offset:33792
	ds_read_b128 v[162:165], v0 offset:35840
	s_waitcnt lgkmcnt(2)
; #define MFMA16(a, b, c) __builtin_amdgcn_mfma_f32_16x16x32_bf16((a), (b), (c), 0, 0, 0)
; template <class Epi>
; DI void gemm8_tile(const bf16_t* __restrict__ Ab, int lda, const bf16_t* __restrict__ Bb, int ldb, int K, int brow, int bcol, const Epi epi,
;                    bool staged, bool has_next, const bf16_t* __restrict__ Abn, const bf16_t* __restrict__ Bbn) {
;     ...
; #pragma unroll
;     for (int ks = 0; ks < 2; ++ks) {
;       bf16x8 At[8], Bf[4];
;       Bf[0] = *(const bf16x8*)(sb + lds_byte2(wc * 64 + fr, ks * 32 + fq * 8));
;       At[0] = *(const bf16x8*)(sa + lds_byte2(wr * 128 + fr, ks * 32 + fq * 8));
; #pragma unroll
;       for (int n = 1; n < 4; ++n) Bf[n] = *(const bf16x8*)(sb + lds_byte2(wc * 64 + n * 16 + fr, ks * 32 + fq * 8));
; #pragma unroll
;       for (int m = 1; m < 8; ++m) At[m] = *(const bf16x8*)(sa + lds_byte2(wr * 128 + m * 16 + fr, ks * 32 + fq * 8));
;       {
;         __builtin_amdgcn_sched_barrier(0);
;         if (t + 1 < nt) { G8_STAGE_R(cur ^ 1, Ab + (t + 1) * 64, Bb + (t + 1) * 64, 2 * ks, 2 * ks + 2); }
;         else if (has_next) { G8_STAGE_R(0, Abn, Bbn, 2 * ks, 2 * ks + 2); }
;         __builtin_amdgcn_sched_barrier(0);
;       }
; #pragma unroll
;       for (int m = 0; m < 8; ++m)
; #pragma unroll
;         for (int n = 0; n < 4; ++n) acc[m][n] = MFMA16(At[m], Bf[n], acc[m][n]);
;       __builtin_amdgcn_sched_barrier(0);
;     }
;     asm volatile("s_waitcnt vmcnt(0)" ::: "memory");
;     __syncthreads();
	v_mfma_f32_16x16x32_bf16 v[118:121], v[174:177], v[166:169], 0
	v_mfma_f32_16x16x32_bf16 v[114:117], v[174:177], v[170:173], 0
	ds_read_b128 v[174:177], v157 offset:1024
	v_mfma_f32_16x16x32_bf16 v[102:105], v[186:189], v[166:169], 0
	v_mfma_f32_16x16x32_bf16 v[98:101], v[186:189], v[170:173], 0
	ds_read_b128 v[186:189], v207 offset:1024
	v_mfma_f32_16x16x32_bf16 v[86:89], v[190:193], v[166:169], 0
	v_mfma_f32_16x16x32_bf16 v[82:85], v[190:193], v[170:173], 0
	ds_read_b128 v[190:193], v238 offset:1024
	v_mfma_f32_16x16x32_bf16 v[70:73], v[212:215], v[166:169], 0
	v_mfma_f32_16x16x32_bf16 v[66:69], v[212:215], v[170:173], 0
	ds_read_b128 v[212:215], v239 offset:1024
	v_mfma_f32_16x16x32_bf16 v[54:57], v[222:225], v[166:169], 0
	v_mfma_f32_16x16x32_bf16 v[50:53], v[222:225], v[170:173], 0
	ds_read_b128 v[222:225], v240 offset:1024
	v_mfma_f32_16x16x32_bf16 v[38:41], v[226:229], v[166:169], 0
	v_mfma_f32_16x16x32_bf16 v[34:37], v[226:229], v[170:173], 0
	ds_read_b128 v[226:229], v241 offset:1024
	v_mfma_f32_16x16x32_bf16 v[22:25], v[230:233], v[166:169], 0
	v_mfma_f32_16x16x32_bf16 v[18:21], v[230:233], v[170:173], 0
	ds_read_b128 v[230:233], v242 offset:1024
	v_mfma_f32_16x16x32_bf16 v[6:9], v[234:237], v[166:169], 0
	v_mfma_f32_16x16x32_bf16 v[2:5], v[234:237], v[170:173], 0
	ds_read_b128 v[234:237], v243 offset:1024
	ds_read_b128 v[166:169], v0 offset:37888
	ds_read_b128 v[170:173], v0 offset:39936
	s_waitcnt lgkmcnt(8)
	v_mfma_f32_16x16x32_bf16 v[126:129], v[174:177], v[158:161], v[126:129]
	v_mfma_f32_16x16x32_bf16 v[122:125], v[174:177], v[162:165], v[122:125]
	v_add3_u32 v0, s58, v155, v153
	v_mfma_f32_16x16x32_bf16 v[110:113], v[186:189], v[158:161], v[110:113]
	v_mfma_f32_16x16x32_bf16 v[106:109], v[186:189], v[162:165], v[106:109]
	v_add3_u32 v157, s58, v155, v156
	s_waitcnt lgkmcnt(6)
	v_mfma_f32_16x16x32_bf16 v[94:97], v[190:193], v[158:161], v[94:97]
	v_mfma_f32_16x16x32_bf16 v[90:93], v[190:193], v[162:165], v[90:93]
	v_add3_u32 v238, s58, v154, v152
	v_mfma_f32_16x16x32_bf16 v[78:81], v[212:215], v[158:161], v[78:81]
	v_mfma_f32_16x16x32_bf16 v[74:77], v[212:215], v[162:165], v[74:77]
	v_add3_u32 v240, s58, v154, v149
	s_waitcnt lgkmcnt(4)
	v_mfma_f32_16x16x32_bf16 v[62:65], v[222:225], v[158:161], v[62:65]
	v_mfma_f32_16x16x32_bf16 v[58:61], v[222:225], v[162:165], v[58:61]
	v_add3_u32 v242, s58, v154, v147
	v_mfma_f32_16x16x32_bf16 v[46:49], v[226:229], v[158:161], v[46:49]
	v_mfma_f32_16x16x32_bf16 v[42:45], v[226:229], v[162:165], v[42:45]
	v_add3_u32 v207, s58, v154, v150
	s_waitcnt lgkmcnt(2)
	v_mfma_f32_16x16x32_bf16 v[30:33], v[230:233], v[158:161], v[30:33]
	v_mfma_f32_16x16x32_bf16 v[26:29], v[230:233], v[162:165], v[26:29]
	v_add3_u32 v239, s58, v154, v151
	v_mfma_f32_16x16x32_bf16 v[14:17], v[234:237], v[158:161], v[14:17]
	v_mfma_f32_16x16x32_bf16 v[10:13], v[234:237], v[162:165], v[10:13]
	v_add3_u32 v241, s58, v154, v148
	v_add3_u32 v243, s58, v154, v146
	s_waitcnt vmcnt(0) lgkmcnt(0)
	s_barrier
	ds_read_b128 v[158:161], v0 offset:32768
	ds_read_b128 v[162:165], v0 offset:34816
	v_mfma_f32_16x16x32_bf16 v[118:121], v[174:177], v[166:169], v[118:121]
	v_mfma_f32_16x16x32_bf16 v[114:117], v[174:177], v[170:173], v[114:117]
	ds_read_b128 v[174:177], v157
	v_mfma_f32_16x16x32_bf16 v[102:105], v[186:189], v[166:169], v[102:105]
	v_mfma_f32_16x16x32_bf16 v[98:101], v[186:189], v[170:173], v[98:101]
	ds_read_b128 v[186:189], v207
	v_mfma_f32_16x16x32_bf16 v[86:89], v[190:193], v[166:169], v[86:89]
	v_mfma_f32_16x16x32_bf16 v[82:85], v[190:193], v[170:173], v[82:85]
	ds_read_b128 v[190:193], v238
	v_mfma_f32_16x16x32_bf16 v[70:73], v[212:215], v[166:169], v[70:73]
	v_mfma_f32_16x16x32_bf16 v[66:69], v[212:215], v[170:173], v[66:69]
	ds_read_b128 v[212:215], v239
	v_mfma_f32_16x16x32_bf16 v[54:57], v[222:225], v[166:169], v[54:57]
	v_mfma_f32_16x16x32_bf16 v[50:53], v[222:225], v[170:173], v[50:53]
	ds_read_b128 v[222:225], v240
	v_mfma_f32_16x16x32_bf16 v[38:41], v[226:229], v[166:169], v[38:41]
	v_mfma_f32_16x16x32_bf16 v[34:37], v[226:229], v[170:173], v[34:37]
	ds_read_b128 v[226:229], v241
	v_mfma_f32_16x16x32_bf16 v[22:25], v[230:233], v[166:169], v[22:25]
	v_mfma_f32_16x16x32_bf16 v[18:21], v[230:233], v[170:173], v[18:21]
	ds_read_b128 v[230:233], v242
	v_mfma_f32_16x16x32_bf16 v[6:9], v[234:237], v[166:169], v[6:9]
	v_mfma_f32_16x16x32_bf16 v[2:5], v[234:237], v[170:173], v[2:5]
	ds_read_b128 v[234:237], v243
	ds_read_b128 v[166:169], v0 offset:36864
	ds_read_b128 v[170:173], v0 offset:38912
	s_add_u32 s0, s0, 0x80
	s_addc_u32 s1, s1, 0
	s_add_i32 s56, s56, 0x10000

; #define MFMA16(a, b, c) __builtin_amdgcn_mfma_f32_16x16x32_bf16((a), (b), (c), 0, 0, 0)
; #define G8_STAGE(buf_, ap_, bp_) G8_STAGE_R(buf_, ap_, bp_, 0, 4)
; template <class Epi>
; DI void gemm8_tile(const bf16_t* __restrict__ Ab, int lda, const bf16_t* __restrict__ Bb, int ldb, int K, int brow, int bcol, const Epi epi,
;                    bool staged, bool has_next, const bf16_t* __restrict__ Abn, const bf16_t* __restrict__ Bbn) {
;     ...
;   for (int i = 0; i < 4; ++i) { int R, C; stage_rc2(wid * 1024 + i * 8192 + lane * 16, R, C); aoff[i] = (unsigned)R * (unsigned)lda + (unsigned)C; boff[i] = (unsigned)R * (unsigned)ldb + (unsigned)C; }
;     ...
;   f32x4 acc[8][4];
; #pragma unroll
;   for (int m = 0; m < 8; ++m)
; #pragma unroll
;     for (int n = 0; n < 4; ++n) acc[m][n] = (f32x4){0.f, 0.f, 0.f, 0.f};
;   const int nt = K / 64;
;   if (!staged) {
;     G8_STAGE(0, Ab, Bb);
;     asm volatile("s_waitcnt vmcnt(0)" ::: "memory");
;     __syncthreads();
;   }
;   for (int t = 0; t < nt; ++t) {
;     const int cur = t & 1;
;     const unsigned char* sa = smem + cur * G8_STAGE_B;
;     const unsigned char* sb = sa + G8_TILE_B;
; #pragma unroll
;     for (int ks = 0; ks < 2; ++ks) {
;       bf16x8 At[8], Bf[4];
;       Bf[0] = *(const bf16x8*)(sb + lds_byte2(wc * 64 + fr, ks * 32 + fq * 8));
;       At[0] = *(const bf16x8*)(sa + lds_byte2(wr * 128 + fr, ks * 32 + fq * 8));
; #pragma unroll
;       for (int n = 1; n < 4; ++n) Bf[n] = *(const bf16x8*)(sb + lds_byte2(wc * 64 + n * 16 + fr, ks * 32 + fq * 8));
; #pragma unroll
;       for (int m = 1; m < 8; ++m) At[m] = *(const bf16x8*)(sa + lds_byte2(wr * 128 + m * 16 + fr, ks * 32 + fq * 8));
;       {
;         __builtin_amdgcn_sched_barrier(0);
;         if (t + 1 < nt) { G8_STAGE_R(cur ^ 1, Ab + (t + 1) * 64, Bb + (t + 1) * 64, 2 * ks, 2 * ks + 2); }
;         else if (has_next) { G8_STAGE_R(0, Abn, Bbn, 2 * ks, 2 * ks + 2); }
;         __builtin_amdgcn_sched_barrier(0);
;       }
; #pragma unroll
;       for (int m = 0; m < 8; ++m)
; #pragma unroll
;         for (int n = 0; n < 4; ++n) acc[m][n] = MFMA16(At[m], Bf[n], acc[m][n]);
.LBB0_649:
	s_add_u32 s0, s56, s79
	v_lshlrev_b64 v[190:191], 1, v[0:1]
	s_addc_u32 s1, s57, s81
	v_lshlrev_b64 v[192:193], 1, v[6:7]
	v_lshlrev_b64 v[178:179], 1, v[4:5]
	v_lshlrev_b64 v[180:181], 1, v[2:3]
	v_lshl_add_u64 v[130:131], s[0:1], 0, v[190:191]
	v_lshl_add_u64 v[132:133], s[0:1], 0, v[192:193]
	v_lshl_add_u64 v[134:135], s[0:1], 0, v[178:179]
	v_lshl_add_u64 v[136:137], s[0:1], 0, v[180:181]
	s_lshl_b32 s0, s59, 3
	s_add_i32 s0, s28, s0
	s_add_i32 s0, s0, s78
	s_lshl_b32 s1, s31, 3
	s_sub_i32 s0, s0, s1
	v_and_b32_e32 v200, 3, v8
	v_ashrrev_i32_e32 v8, 8, v195
	s_lshl_b32 s1, s0, 8
	s_mul_i32 s0, s0, 0x88000
	v_readlane_b32 s4, v253, 6
	v_and_b32_e32 v194, 15, v195
	v_lshlrev_b32_e32 v11, 2, v195
	v_lshlrev_b32_e32 v201, 7, v8
	v_lshlrev_b32_e32 v156, 14, v8
	v_lshlrev_b32_e32 v8, 6, v195
	s_mul_hi_i32 s1, s1, 0x880
	s_add_u32 s0, s4, s0
	v_readlane_b32 s4, v253, 7
	v_and_b32_e32 v9, 48, v195
	v_lshlrev_b32_e32 v10, 6, v194
	v_and_b32_e32 v11, 32, v11
	v_and_b32_e32 v8, 0x3c0, v8
	s_addc_u32 s1, s4, s1
	v_lshlrev_b32_e32 v153, 13, v200
	v_bitop3_b32 v155, v10, v11, v9 bitop3:0x36
	v_or_b32_e32 v150, 0x800, v156
	v_bitop3_b32 v154, v8, v11, v9 bitop3:0x36
	v_or_b32_e32 v152, 0x1000, v156
	v_or_b32_e32 v151, 0x1800, v156
	v_or_b32_e32 v149, 0x2000, v156
	v_or_b32_e32 v148, 0x2800, v156
	v_or_b32_e32 v147, 0x3000, v156
	v_or_b32_e32 v146, 0x3800, v156
	v_lshl_add_u64 v[138:139], s[0:1], 0, v[190:191]
	v_lshl_add_u64 v[140:141], s[0:1], 0, v[192:193]
	v_lshl_add_u64 v[142:143], s[0:1], 0, v[178:179]
	v_lshl_add_u64 v[144:145], s[0:1], 0, v[180:181]
	s_mov_b64 s[0:1], 0
	s_mov_b32 s14, 0
	s_waitcnt vmcnt(8)
	s_mov_b32 s31, 0
	v_add3_u32 v0, s31, v155, v153
	v_add3_u32 v157, s31, v155, v156
	v_add3_u32 v237, s31, v154, v152
	v_add3_u32 v239, s31, v154, v149
	v_add3_u32 v241, s31, v154, v147
	v_add3_u32 v236, s31, v154, v150
	v_add3_u32 v238, s31, v154, v151
	v_add3_u32 v240, s31, v154, v148
	v_add3_u32 v242, s31, v154, v146
	ds_read_b128 v[158:161], v0 offset:32768
	ds_read_b128 v[162:165], v0 offset:34816
	ds_read_b128 v[174:177], v157
	ds_read_b128 v[186:189], v236
	ds_read_b128 v[202:205], v237
	ds_read_b128 v[206:209], v238
	ds_read_b128 v[212:215], v239
	ds_read_b128 v[222:225], v240
	ds_read_b128 v[226:229], v241
	ds_read_b128 v[230:233], v242
	ds_read_b128 v[166:169], v0 offset:36864
	ds_read_b128 v[170:173], v0 offset:38912
	s_and_b32 s15, s14, 0x10000
	s_xor_b32 s31, s15, 0x10000
	v_add_u32_e32 v243, s31, v185
	s_nop 0
	v_readfirstlane_b32 s15, v243
	s_waitcnt lgkmcnt(8)
	v_mfma_f32_16x16x32_bf16 v[126:129], v[174:177], v[158:161], 0
	v_mfma_f32_16x16x32_bf16 v[122:125], v[174:177], v[162:165], 0
	s_mov_b32 m0, s15
	v_lshl_add_u64 v[234:235], v[144:145], 0, s[0:1]
	global_load_lds_dwordx4 v[234:235], off
	v_mfma_f32_16x16x32_bf16 v[110:113], v[186:189], v[158:161], 0
	v_mfma_f32_16x16x32_bf16 v[106:109], v[186:189], v[162:165], 0
	s_add_u32 m0, s15, 0x8000
	v_lshl_add_u64 v[234:235], v[136:137], 0, s[0:1]
	global_load_lds_dwordx4 v[234:235], off
	s_waitcnt lgkmcnt(6)
	v_mfma_f32_16x16x32_bf16 v[94:97], v[202:205], v[158:161], 0
	v_mfma_f32_16x16x32_bf16 v[90:93], v[202:205], v[162:165], 0
	s_add_u32 m0, s15, 0x2000
	v_lshl_add_u64 v[234:235], v[142:143], 0, s[0:1]
	global_load_lds_dwordx4 v[234:235], off
	v_mfma_f32_16x16x32_bf16 v[78:81], v[206:209], v[158:161], 0
	v_mfma_f32_16x16x32_bf16 v[74:77], v[206:209], v[162:165], 0
	s_add_u32 m0, s15, 0xa000
	v_lshl_add_u64 v[234:235], v[134:135], 0, s[0:1]
	global_load_lds_dwordx4 v[234:235], off
	s_waitcnt lgkmcnt(4)
	v_mfma_f32_16x16x32_bf16 v[62:65], v[212:215], v[158:161], 0
	v_mfma_f32_16x16x32_bf16 v[58:61], v[212:215], v[162:165], 0
	s_add_u32 m0, s15, 0x4000
	v_lshl_add_u64 v[234:235], v[140:141], 0, s[0:1]
	global_load_lds_dwordx4 v[234:235], off
	v_mfma_f32_16x16x32_bf16 v[46:49], v[222:225], v[158:161], 0
	v_mfma_f32_16x16x32_bf16 v[42:45], v[222:225], v[162:165], 0
	s_add_u32 m0, s15, 0xc000
	v_lshl_add_u64 v[234:235], v[132:133], 0, s[0:1]
	global_load_lds_dwordx4 v[234:235], off
	s_waitcnt lgkmcnt(2)
	v_mfma_f32_16x16x32_bf16 v[30:33], v[226:229], v[158:161], 0
	v_mfma_f32_16x16x32_bf16 v[26:29], v[226:229], v[162:165], 0
	s_add_u32 m0, s15, 0x6000
	v_lshl_add_u64 v[234:235], v[138:139], 0, s[0:1]
	global_load_lds_dwordx4 v[234:235], off
	v_mfma_f32_16x16x32_bf16 v[14:17], v[230:233], v[158:161], 0
	v_mfma_f32_16x16x32_bf16 v[10:13], v[230:233], v[162:165], 0
	s_add_u32 m0, s15, 0xe000
	v_lshl_add_u64 v[234:235], v[130:131], 0, s[0:1]
	global_load_lds_dwordx4 v[234:235], off
	ds_read_b128 v[158:161], v0 offset:33792
	ds_read_b128 v[162:165], v0 offset:35840
	s_waitcnt lgkmcnt(2)
; #define MFMA16(a, b, c) __builtin_amdgcn_mfma_f32_16x16x32_bf16((a), (b), (c), 0, 0, 0)
; template <class Epi>
; DI void gemm8_tile(const bf16_t* __restrict__ Ab, int lda, const bf16_t* __restrict__ Bb, int ldb, int K, int brow, int bcol, const Epi epi,
;                    bool staged, bool has_next, const bf16_t* __restrict__ Abn, const bf16_t* __restrict__ Bbn) {
;     ...
; #pragma unroll
;     for (int ks = 0; ks < 2; ++ks) {
;       bf16x8 At[8], Bf[4];
;       Bf[0] = *(const bf16x8*)(sb + lds_byte2(wc * 64 + fr, ks * 32 + fq * 8));
;       At[0] = *(const bf16x8*)(sa + lds_byte2(wr * 128 + fr, ks * 32 + fq * 8));
; #pragma unroll
;       for (int n = 1; n < 4; ++n) Bf[n] = *(const bf16x8*)(sb + lds_byte2(wc * 64 + n * 16 + fr, ks * 32 + fq * 8));
; #pragma unroll
;       for (int m = 1; m < 8; ++m) At[m] = *(const bf16x8*)(sa + lds_byte2(wr * 128 + m * 16 + fr, ks * 32 + fq * 8));
;       {
;         __builtin_amdgcn_sched_barrier(0);
;         if (t + 1 < nt) { G8_STAGE_R(cur ^ 1, Ab + (t + 1) * 64, Bb + (t + 1) * 64, 2 * ks, 2 * ks + 2); }
;         else if (has_next) { G8_STAGE_R(0, Abn, Bbn, 2 * ks, 2 * ks + 2); }
;         __builtin_amdgcn_sched_barrier(0);
;       }
; #pragma unroll
;       for (int m = 0; m < 8; ++m)
; #pragma unroll
;         for (int n = 0; n < 4; ++n) acc[m][n] = MFMA16(At[m], Bf[n], acc[m][n]);
;       __builtin_amdgcn_sched_barrier(0);
;     }
;     asm volatile("s_waitcnt vmcnt(0)" ::: "memory");
;     __syncthreads();
	v_mfma_f32_16x16x32_bf16 v[118:121], v[174:177], v[166:169], 0
	v_mfma_f32_16x16x32_bf16 v[114:117], v[174:177], v[170:173], 0
	ds_read_b128 v[174:177], v157 offset:1024
	v_mfma_f32_16x16x32_bf16 v[102:105], v[186:189], v[166:169], 0
	v_mfma_f32_16x16x32_bf16 v[98:101], v[186:189], v[170:173], 0
	ds_read_b128 v[186:189], v236 offset:1024
	v_mfma_f32_16x16x32_bf16 v[86:89], v[202:205], v[166:169], 0
	v_mfma_f32_16x16x32_bf16 v[82:85], v[202:205], v[170:173], 0
	ds_read_b128 v[202:205], v237 offset:1024
	v_mfma_f32_16x16x32_bf16 v[70:73], v[206:209], v[166:169], 0
	v_mfma_f32_16x16x32_bf16 v[66:69], v[206:209], v[170:173], 0
	ds_read_b128 v[206:209], v238 offset:1024
	v_mfma_f32_16x16x32_bf16 v[54:57], v[212:215], v[166:169], 0
	v_mfma_f32_16x16x32_bf16 v[50:53], v[212:215], v[170:173], 0
	ds_read_b128 v[212:215], v239 offset:1024
	v_mfma_f32_16x16x32_bf16 v[38:41], v[222:225], v[166:169], 0
	v_mfma_f32_16x16x32_bf16 v[34:37], v[222:225], v[170:173], 0
	ds_read_b128 v[222:225], v240 offset:1024
	v_mfma_f32_16x16x32_bf16 v[22:25], v[226:229], v[166:169], 0
	v_mfma_f32_16x16x32_bf16 v[18:21], v[226:229], v[170:173], 0
	ds_read_b128 v[226:229], v241 offset:1024
	v_mfma_f32_16x16x32_bf16 v[6:9], v[230:233], v[166:169], 0
	v_mfma_f32_16x16x32_bf16 v[2:5], v[230:233], v[170:173], 0
	ds_read_b128 v[230:233], v242 offset:1024
	ds_read_b128 v[166:169], v0 offset:37888
	ds_read_b128 v[170:173], v0 offset:39936
	s_waitcnt lgkmcnt(8)
	v_mfma_f32_16x16x32_bf16 v[126:129], v[174:177], v[158:161], v[126:129]
	v_mfma_f32_16x16x32_bf16 v[122:125], v[174:177], v[162:165], v[122:125]
	v_add3_u32 v0, s31, v155, v153
	v_mfma_f32_16x16x32_bf16 v[110:113], v[186:189], v[158:161], v[110:113]
	v_mfma_f32_16x16x32_bf16 v[106:109], v[186:189], v[162:165], v[106:109]
	v_add3_u32 v157, s31, v155, v156
	s_waitcnt lgkmcnt(6)
	v_mfma_f32_16x16x32_bf16 v[94:97], v[202:205], v[158:161], v[94:97]
	v_mfma_f32_16x16x32_bf16 v[90:93], v[202:205], v[162:165], v[90:93]
	v_add3_u32 v237, s31, v154, v152
	v_mfma_f32_16x16x32_bf16 v[78:81], v[206:209], v[158:161], v[78:81]
	v_mfma_f32_16x16x32_bf16 v[74:77], v[206:209], v[162:165], v[74:77]
	v_add3_u32 v239, s31, v154, v149
	s_waitcnt lgkmcnt(4)
	v_mfma_f32_16x16x32_bf16 v[62:65], v[212:215], v[158:161], v[62:65]
	v_mfma_f32_16x16x32_bf16 v[58:61], v[212:215], v[162:165], v[58:61]
	v_add3_u32 v241, s31, v154, v147
	v_mfma_f32_16x16x32_bf16 v[46:49], v[222:225], v[158:161], v[46:49]
	v_mfma_f32_16x16x32_bf16 v[42:45], v[222:225], v[162:165], v[42:45]
	v_add3_u32 v236, s31, v154, v150
	s_waitcnt lgkmcnt(2)
	v_mfma_f32_16x16x32_bf16 v[30:33], v[226:229], v[158:161], v[30:33]
	v_mfma_f32_16x16x32_bf16 v[26:29], v[226:229], v[162:165], v[26:29]
	v_add3_u32 v238, s31, v154, v151
	v_mfma_f32_16x16x32_bf16 v[14:17], v[230:233], v[158:161], v[14:17]
	v_mfma_f32_16x16x32_bf16 v[10:13], v[230:233], v[162:165], v[10:13]
	v_add3_u32 v240, s31, v154, v148
	v_add3_u32 v242, s31, v154, v146
	s_waitcnt vmcnt(0) lgkmcnt(0)
	s_barrier
	ds_read_b128 v[158:161], v0 offset:32768
	ds_read_b128 v[162:165], v0 offset:34816
	v_mfma_f32_16x16x32_bf16 v[118:121], v[174:177], v[166:169], v[118:121]
	v_mfma_f32_16x16x32_bf16 v[114:117], v[174:177], v[170:173], v[114:117]
	ds_read_b128 v[174:177], v157
	v_mfma_f32_16x16x32_bf16 v[102:105], v[186:189], v[166:169], v[102:105]
	v_mfma_f32_16x16x32_bf16 v[98:101], v[186:189], v[170:173], v[98:101]
	ds_read_b128 v[186:189], v236
	v_mfma_f32_16x16x32_bf16 v[86:89], v[202:205], v[166:169], v[86:89]
	v_mfma_f32_16x16x32_bf16 v[82:85], v[202:205], v[170:173], v[82:85]
	ds_read_b128 v[202:205], v237
	v_mfma_f32_16x16x32_bf16 v[70:73], v[206:209], v[166:169], v[70:73]
	v_mfma_f32_16x16x32_bf16 v[66:69], v[206:209], v[170:173], v[66:69]
	ds_read_b128 v[206:209], v238
	v_mfma_f32_16x16x32_bf16 v[54:57], v[212:215], v[166:169], v[54:57]
	v_mfma_f32_16x16x32_bf16 v[50:53], v[212:215], v[170:173], v[50:53]
	ds_read_b128 v[212:215], v239
	v_mfma_f32_16x16x32_bf16 v[38:41], v[222:225], v[166:169], v[38:41]
	v_mfma_f32_16x16x32_bf16 v[34:37], v[222:225], v[170:173], v[34:37]
	ds_read_b128 v[222:225], v240
	v_mfma_f32_16x16x32_bf16 v[22:25], v[226:229], v[166:169], v[22:25]
	v_mfma_f32_16x16x32_bf16 v[18:21], v[226:229], v[170:173], v[18:21]
	ds_read_b128 v[226:229], v241
	v_mfma_f32_16x16x32_bf16 v[6:9], v[230:233], v[166:169], v[6:9]
	v_mfma_f32_16x16x32_bf16 v[2:5], v[230:233], v[170:173], v[2:5]
	ds_read_b128 v[230:233], v242
	ds_read_b128 v[166:169], v0 offset:36864
	ds_read_b128 v[170:173], v0 offset:38912
	s_add_u32 s0, s0, 0x80
	s_addc_u32 s1, s1, 0
	s_add_i32 s14, s14, 0x10000

; #define MFMA16(a, b, c) __builtin_amdgcn_mfma_f32_16x16x32_bf16((a), (b), (c), 0, 0, 0)
; #define G8_STAGE(buf_, ap_, bp_) G8_STAGE_R(buf_, ap_, bp_, 0, 4)
; template <class Epi>
; DI void gemm8_tile(const bf16_t* __restrict__ Ab, int lda, const bf16_t* __restrict__ Bb, int ldb, int K, int brow, int bcol, const Epi epi,
;                    bool staged, bool has_next, const bf16_t* __restrict__ Abn, const bf16_t* __restrict__ Bbn) {
;     ...
;   for (int i = 0; i < 4; ++i) { int R, C; stage_rc2(wid * 1024 + i * 8192 + lane * 16, R, C); aoff[i] = (unsigned)R * (unsigned)lda + (unsigned)C; boff[i] = (unsigned)R * (unsigned)ldb + (unsigned)C; }
;     ...
;   f32x4 acc[8][4];
; #pragma unroll
;   for (int m = 0; m < 8; ++m)
; #pragma unroll
;     for (int n = 0; n < 4; ++n) acc[m][n] = (f32x4){0.f, 0.f, 0.f, 0.f};
;   const int nt = K / 64;
;   if (!staged) {
;     G8_STAGE(0, Ab, Bb);
;     asm volatile("s_waitcnt vmcnt(0)" ::: "memory");
;     __syncthreads();
;   }
;   for (int t = 0; t < nt; ++t) {
;     const int cur = t & 1;
;     const unsigned char* sa = smem + cur * G8_STAGE_B;
;     const unsigned char* sb = sa + G8_TILE_B;
; #pragma unroll
;     for (int ks = 0; ks < 2; ++ks) {
;       bf16x8 At[8], Bf[4];
;       Bf[0] = *(const bf16x8*)(sb + lds_byte2(wc * 64 + fr, ks * 32 + fq * 8));
;       At[0] = *(const bf16x8*)(sa + lds_byte2(wr * 128 + fr, ks * 32 + fq * 8));
; #pragma unroll
;       for (int n = 1; n < 4; ++n) Bf[n] = *(const bf16x8*)(sb + lds_byte2(wc * 64 + n * 16 + fr, ks * 32 + fq * 8));
; #pragma unroll
;       for (int m = 1; m < 8; ++m) At[m] = *(const bf16x8*)(sa + lds_byte2(wr * 128 + m * 16 + fr, ks * 32 + fq * 8));
;       {
;         __builtin_amdgcn_sched_barrier(0);
;         if (t + 1 < nt) { G8_STAGE_R(cur ^ 1, Ab + (t + 1) * 64, Bb + (t + 1) * 64, 2 * ks, 2 * ks + 2); }
;         else if (has_next) { G8_STAGE_R(0, Abn, Bbn, 2 * ks, 2 * ks + 2); }
;         __builtin_amdgcn_sched_barrier(0);
;       }
; #pragma unroll
;       for (int m = 0; m < 8; ++m)
; #pragma unroll
;         for (int n = 0; n < 4; ++n) acc[m][n] = MFMA16(At[m], Bf[n], acc[m][n]);
.LBB0_1253:
	s_add_u32 s0, s57, s81
	s_addc_u32 s1, s58, s87
	v_lshl_add_u64 v[130:131], v[0:1], 1, s[0:1]
	v_lshl_add_u64 v[132:133], v[180:181], 1, s[0:1]
	v_lshl_add_u64 v[134:135], v[190:191], 1, s[0:1]
	v_lshl_add_u64 v[136:137], v[186:187], 1, s[0:1]
	s_lshl_b32 s0, s78, 3
	s_add_i32 s0, s28, s0
	s_add_i32 s0, s0, s79
	s_lshl_b32 s1, s75, 3
	s_sub_i32 s0, s0, s1
	v_and_b32_e32 v198, 3, v3
	v_ashrrev_i32_e32 v3, 8, v2
	v_and_b32_e32 v197, 15, v2
	v_and_b32_e32 v4, 48, v2
	v_lshlrev_b32_e32 v6, 2, v2
	v_lshlrev_b32_e32 v2, 6, v2
	s_lshl_b32 s1, s0, 8
	s_mul_i32 s0, s0, 0x88000
	v_and_b32_e32 v6, 32, v6
	v_and_b32_e32 v2, 0x3c0, v2
	s_mul_hi_i32 s1, s1, 0x880
	s_add_u32 s0, s91, s0
	v_lshlrev_b32_e32 v5, 6, v197
	v_lshlrev_b32_e32 v156, 14, v3
	v_bitop3_b32 v154, v2, v6, v4 bitop3:0x36
	s_addc_u32 s1, s72, s1
	v_lshlrev_b32_e32 v153, 13, v198
	v_bitop3_b32 v155, v5, v6, v4 bitop3:0x36
	v_lshlrev_b32_e32 v199, 7, v3
	v_or_b32_e32 v150, 0x800, v156
	v_or_b32_e32 v152, 0x1000, v156
	v_or_b32_e32 v151, 0x1800, v156
	v_or_b32_e32 v149, 0x2000, v156
	v_or_b32_e32 v148, 0x2800, v156
	v_or_b32_e32 v147, 0x3000, v156
	v_or_b32_e32 v146, 0x3800, v156
	v_lshl_add_u64 v[138:139], v[182:183], 1, s[0:1]
	v_lshl_add_u64 v[140:141], v[178:179], 1, s[0:1]
	v_lshl_add_u64 v[142:143], v[188:189], 1, s[0:1]
	v_lshl_add_u64 v[144:145], v[184:185], 1, s[0:1]
	s_mov_b64 s[0:1], 0
	s_mov_b32 s38, 0
	s_waitcnt vmcnt(8)
	s_mov_b32 s54, 0
	v_add3_u32 v157, s54, v155, v153
	v_add3_u32 v242, s54, v155, v156
	v_add3_u32 v244, s54, v154, v152
	v_add3_u32 v246, s54, v154, v149
	v_add3_u32 v248, s54, v154, v147
	v_add3_u32 v243, s54, v154, v150
	v_add3_u32 v245, s54, v154, v151
	v_add3_u32 v247, s54, v154, v148
	v_add3_u32 v249, s54, v154, v146
	ds_read_b128 v[158:161], v157 offset:32768
	ds_read_b128 v[162:165], v157 offset:34816
	ds_read_b128 v[174:177], v242
	ds_read_b128 v[204:207], v243
	ds_read_b128 v[212:215], v244
	ds_read_b128 v[222:225], v245
	ds_read_b128 v[226:229], v246
	ds_read_b128 v[230:233], v247
	ds_read_b128 v[234:237], v248
	ds_read_b128 v[238:241], v249
	ds_read_b128 v[166:169], v157 offset:36864
	ds_read_b128 v[170:173], v157 offset:38912
	s_and_b32 s39, s38, 0x10000
	s_xor_b32 s54, s39, 0x10000
	v_add_u32_e32 v250, s54, v203
	s_nop 0
	v_readfirstlane_b32 s39, v250
	s_waitcnt lgkmcnt(8)
	v_mfma_f32_16x16x32_bf16 v[126:129], v[174:177], v[158:161], 0
	v_mfma_f32_16x16x32_bf16 v[122:125], v[174:177], v[162:165], 0
	s_mov_b32 m0, s39
	v_lshl_add_u64 v[208:209], v[144:145], 0, s[0:1]
	global_load_lds_dwordx4 v[208:209], off
	v_mfma_f32_16x16x32_bf16 v[110:113], v[204:207], v[158:161], 0
	v_mfma_f32_16x16x32_bf16 v[106:109], v[204:207], v[162:165], 0
	s_add_u32 m0, s39, 0x8000
	v_lshl_add_u64 v[208:209], v[136:137], 0, s[0:1]
	global_load_lds_dwordx4 v[208:209], off
	s_waitcnt lgkmcnt(6)
	v_mfma_f32_16x16x32_bf16 v[94:97], v[212:215], v[158:161], 0
	v_mfma_f32_16x16x32_bf16 v[90:93], v[212:215], v[162:165], 0
	s_add_u32 m0, s39, 0x2000
	v_lshl_add_u64 v[208:209], v[142:143], 0, s[0:1]
	global_load_lds_dwordx4 v[208:209], off
	v_mfma_f32_16x16x32_bf16 v[78:81], v[222:225], v[158:161], 0
	v_mfma_f32_16x16x32_bf16 v[74:77], v[222:225], v[162:165], 0
	s_add_u32 m0, s39, 0xa000
	v_lshl_add_u64 v[208:209], v[134:135], 0, s[0:1]
	global_load_lds_dwordx4 v[208:209], off
	s_waitcnt lgkmcnt(4)
	v_mfma_f32_16x16x32_bf16 v[62:65], v[226:229], v[158:161], 0
	v_mfma_f32_16x16x32_bf16 v[58:61], v[226:229], v[162:165], 0
	s_add_u32 m0, s39, 0x4000
	v_lshl_add_u64 v[208:209], v[140:141], 0, s[0:1]
	global_load_lds_dwordx4 v[208:209], off
	v_mfma_f32_16x16x32_bf16 v[46:49], v[230:233], v[158:161], 0
	v_mfma_f32_16x16x32_bf16 v[42:45], v[230:233], v[162:165], 0
	s_add_u32 m0, s39, 0xc000
	v_lshl_add_u64 v[208:209], v[132:133], 0, s[0:1]
	global_load_lds_dwordx4 v[208:209], off
	s_waitcnt lgkmcnt(2)
	v_mfma_f32_16x16x32_bf16 v[30:33], v[234:237], v[158:161], 0
	v_mfma_f32_16x16x32_bf16 v[26:29], v[234:237], v[162:165], 0
	s_add_u32 m0, s39, 0x6000
	v_lshl_add_u64 v[208:209], v[138:139], 0, s[0:1]
	global_load_lds_dwordx4 v[208:209], off
	v_mfma_f32_16x16x32_bf16 v[14:17], v[238:241], v[158:161], 0
	v_mfma_f32_16x16x32_bf16 v[10:13], v[238:241], v[162:165], 0
	s_add_u32 m0, s39, 0xe000
	v_lshl_add_u64 v[208:209], v[130:131], 0, s[0:1]
	global_load_lds_dwordx4 v[208:209], off
	ds_read_b128 v[158:161], v157 offset:33792
	ds_read_b128 v[162:165], v157 offset:35840
	s_waitcnt lgkmcnt(2)
; #define MFMA16(a, b, c) __builtin_amdgcn_mfma_f32_16x16x32_bf16((a), (b), (c), 0, 0, 0)
; template <class Epi>
; DI void gemm8_tile(const bf16_t* __restrict__ Ab, int lda, const bf16_t* __restrict__ Bb, int ldb, int K, int brow, int bcol, const Epi epi,
;                    bool staged, bool has_next, const bf16_t* __restrict__ Abn, const bf16_t* __restrict__ Bbn) {
;     ...
; #pragma unroll
;     for (int ks = 0; ks < 2; ++ks) {
;       bf16x8 At[8], Bf[4];
;       Bf[0] = *(const bf16x8*)(sb + lds_byte2(wc * 64 + fr, ks * 32 + fq * 8));
;       At[0] = *(const bf16x8*)(sa + lds_byte2(wr * 128 + fr, ks * 32 + fq * 8));
; #pragma unroll
;       for (int n = 1; n < 4; ++n) Bf[n] = *(const bf16x8*)(sb + lds_byte2(wc * 64 + n * 16 + fr, ks * 32 + fq * 8));
; #pragma unroll
;       for (int m = 1; m < 8; ++m) At[m] = *(const bf16x8*)(sa + lds_byte2(wr * 128 + m * 16 + fr, ks * 32 + fq * 8));
;       {
;         __builtin_amdgcn_sched_barrier(0);
;         if (t + 1 < nt) { G8_STAGE_R(cur ^ 1, Ab + (t + 1) * 64, Bb + (t + 1) * 64, 2 * ks, 2 * ks + 2); }
;         else if (has_next) { G8_STAGE_R(0, Abn, Bbn, 2 * ks, 2 * ks + 2); }
;         __builtin_amdgcn_sched_barrier(0);
;       }
; #pragma unroll
;       for (int m = 0; m < 8; ++m)
; #pragma unroll
;         for (int n = 0; n < 4; ++n) acc[m][n] = MFMA16(At[m], Bf[n], acc[m][n]);
;       __builtin_amdgcn_sched_barrier(0);
;     }
;     asm volatile("s_waitcnt vmcnt(0)" ::: "memory");
;     __syncthreads();
	v_mfma_f32_16x16x32_bf16 v[118:121], v[174:177], v[166:169], 0
	v_mfma_f32_16x16x32_bf16 v[114:117], v[174:177], v[170:173], 0
	ds_read_b128 v[174:177], v242 offset:1024
	v_mfma_f32_16x16x32_bf16 v[102:105], v[204:207], v[166:169], 0
	v_mfma_f32_16x16x32_bf16 v[98:101], v[204:207], v[170:173], 0
	ds_read_b128 v[204:207], v243 offset:1024
	v_mfma_f32_16x16x32_bf16 v[86:89], v[212:215], v[166:169], 0
	v_mfma_f32_16x16x32_bf16 v[82:85], v[212:215], v[170:173], 0
	ds_read_b128 v[212:215], v244 offset:1024
	v_mfma_f32_16x16x32_bf16 v[70:73], v[222:225], v[166:169], 0
	v_mfma_f32_16x16x32_bf16 v[66:69], v[222:225], v[170:173], 0
	ds_read_b128 v[222:225], v245 offset:1024
	v_mfma_f32_16x16x32_bf16 v[54:57], v[226:229], v[166:169], 0
	v_mfma_f32_16x16x32_bf16 v[50:53], v[226:229], v[170:173], 0
	ds_read_b128 v[226:229], v246 offset:1024
	v_mfma_f32_16x16x32_bf16 v[38:41], v[230:233], v[166:169], 0
	v_mfma_f32_16x16x32_bf16 v[34:37], v[230:233], v[170:173], 0
	ds_read_b128 v[230:233], v247 offset:1024
	v_mfma_f32_16x16x32_bf16 v[22:25], v[234:237], v[166:169], 0
	v_mfma_f32_16x16x32_bf16 v[18:21], v[234:237], v[170:173], 0
	ds_read_b128 v[234:237], v248 offset:1024
	v_mfma_f32_16x16x32_bf16 v[6:9], v[238:241], v[166:169], 0
	v_mfma_f32_16x16x32_bf16 v[2:5], v[238:241], v[170:173], 0
	ds_read_b128 v[238:241], v249 offset:1024
	ds_read_b128 v[166:169], v157 offset:37888
	ds_read_b128 v[170:173], v157 offset:39936
	s_waitcnt lgkmcnt(8)
	v_mfma_f32_16x16x32_bf16 v[126:129], v[174:177], v[158:161], v[126:129]
	v_mfma_f32_16x16x32_bf16 v[122:125], v[174:177], v[162:165], v[122:125]
	v_add3_u32 v157, s54, v155, v153
	v_mfma_f32_16x16x32_bf16 v[110:113], v[204:207], v[158:161], v[110:113]
	v_mfma_f32_16x16x32_bf16 v[106:109], v[204:207], v[162:165], v[106:109]
	v_add3_u32 v242, s54, v155, v156
	s_waitcnt lgkmcnt(6)
	v_mfma_f32_16x16x32_bf16 v[94:97], v[212:215], v[158:161], v[94:97]
	v_mfma_f32_16x16x32_bf16 v[90:93], v[212:215], v[162:165], v[90:93]
	v_add3_u32 v244, s54, v154, v152
	v_mfma_f32_16x16x32_bf16 v[78:81], v[222:225], v[158:161], v[78:81]
	v_mfma_f32_16x16x32_bf16 v[74:77], v[222:225], v[162:165], v[74:77]
	v_add3_u32 v246, s54, v154, v149
	s_waitcnt lgkmcnt(4)
	v_mfma_f32_16x16x32_bf16 v[62:65], v[226:229], v[158:161], v[62:65]
	v_mfma_f32_16x16x32_bf16 v[58:61], v[226:229], v[162:165], v[58:61]
	v_add3_u32 v248, s54, v154, v147
	v_mfma_f32_16x16x32_bf16 v[46:49], v[230:233], v[158:161], v[46:49]
	v_mfma_f32_16x16x32_bf16 v[42:45], v[230:233], v[162:165], v[42:45]
	v_add3_u32 v243, s54, v154, v150
	s_waitcnt lgkmcnt(2)
	v_mfma_f32_16x16x32_bf16 v[30:33], v[234:237], v[158:161], v[30:33]
	v_mfma_f32_16x16x32_bf16 v[26:29], v[234:237], v[162:165], v[26:29]
	v_add3_u32 v245, s54, v154, v151
	v_mfma_f32_16x16x32_bf16 v[14:17], v[238:241], v[158:161], v[14:17]
	v_mfma_f32_16x16x32_bf16 v[10:13], v[238:241], v[162:165], v[10:13]
	v_add3_u32 v247, s54, v154, v148
	v_add3_u32 v249, s54, v154, v146
	s_waitcnt vmcnt(0) lgkmcnt(0)
	s_barrier
	ds_read_b128 v[158:161], v157 offset:32768
	ds_read_b128 v[162:165], v157 offset:34816
	v_mfma_f32_16x16x32_bf16 v[118:121], v[174:177], v[166:169], v[118:121]
	v_mfma_f32_16x16x32_bf16 v[114:117], v[174:177], v[170:173], v[114:117]
	ds_read_b128 v[174:177], v242
	v_mfma_f32_16x16x32_bf16 v[102:105], v[204:207], v[166:169], v[102:105]
	v_mfma_f32_16x16x32_bf16 v[98:101], v[204:207], v[170:173], v[98:101]
	ds_read_b128 v[204:207], v243
	v_mfma_f32_16x16x32_bf16 v[86:89], v[212:215], v[166:169], v[86:89]
	v_mfma_f32_16x16x32_bf16 v[82:85], v[212:215], v[170:173], v[82:85]
	ds_read_b128 v[212:215], v244
	v_mfma_f32_16x16x32_bf16 v[70:73], v[222:225], v[166:169], v[70:73]
	v_mfma_f32_16x16x32_bf16 v[66:69], v[222:225], v[170:173], v[66:69]
	ds_read_b128 v[222:225], v245
	v_mfma_f32_16x16x32_bf16 v[54:57], v[226:229], v[166:169], v[54:57]
	v_mfma_f32_16x16x32_bf16 v[50:53], v[226:229], v[170:173], v[50:53]
	ds_read_b128 v[226:229], v246
	v_mfma_f32_16x16x32_bf16 v[38:41], v[230:233], v[166:169], v[38:41]
	v_mfma_f32_16x16x32_bf16 v[34:37], v[230:233], v[170:173], v[34:37]
	ds_read_b128 v[230:233], v247
	v_mfma_f32_16x16x32_bf16 v[22:25], v[234:237], v[166:169], v[22:25]
	v_mfma_f32_16x16x32_bf16 v[18:21], v[234:237], v[170:173], v[18:21]
	ds_read_b128 v[234:237], v248
	v_mfma_f32_16x16x32_bf16 v[6:9], v[238:241], v[166:169], v[6:9]
	v_mfma_f32_16x16x32_bf16 v[2:5], v[238:241], v[170:173], v[2:5]
	ds_read_b128 v[238:241], v249
	ds_read_b128 v[166:169], v157 offset:36864
	ds_read_b128 v[170:173], v157 offset:38912
	s_add_u32 s0, s0, 0x80
	s_addc_u32 s1, s1, 0
	s_add_i32 s38, s38, 0x10000

; #define MFMA16(a, b, c) __builtin_amdgcn_mfma_f32_16x16x32_bf16((a), (b), (c), 0, 0, 0)
; #define G8_STAGE(buf_, ap_, bp_) G8_STAGE_R(buf_, ap_, bp_, 0, 4)
; template <class Epi>
; DI void gemm8_tile(const bf16_t* __restrict__ Ab, int lda, const bf16_t* __restrict__ Bb, int ldb, int K, int brow, int bcol, const Epi epi,
;                    bool staged, bool has_next, const bf16_t* __restrict__ Abn, const bf16_t* __restrict__ Bbn) {
;     ...
;   for (int i = 0; i < 4; ++i) { int R, C; stage_rc2(wid * 1024 + i * 8192 + lane * 16, R, C); aoff[i] = (unsigned)R * (unsigned)lda + (unsigned)C; boff[i] = (unsigned)R * (unsigned)ldb + (unsigned)C; }
;     ...
;   f32x4 acc[8][4];
; #pragma unroll
;   for (int m = 0; m < 8; ++m)
; #pragma unroll
;     for (int n = 0; n < 4; ++n) acc[m][n] = (f32x4){0.f, 0.f, 0.f, 0.f};
;   const int nt = K / 64;
;   if (!staged) {
;     G8_STAGE(0, Ab, Bb);
;     asm volatile("s_waitcnt vmcnt(0)" ::: "memory");
;     __syncthreads();
;   }
;   for (int t = 0; t < nt; ++t) {
;     const int cur = t & 1;
;     const unsigned char* sa = smem + cur * G8_STAGE_B;
;     const unsigned char* sb = sa + G8_TILE_B;
; #pragma unroll
;     for (int ks = 0; ks < 2; ++ks) {
;       bf16x8 At[8], Bf[4];
;       Bf[0] = *(const bf16x8*)(sb + lds_byte2(wc * 64 + fr, ks * 32 + fq * 8));
;       At[0] = *(const bf16x8*)(sa + lds_byte2(wr * 128 + fr, ks * 32 + fq * 8));
; #pragma unroll
;       for (int n = 1; n < 4; ++n) Bf[n] = *(const bf16x8*)(sb + lds_byte2(wc * 64 + n * 16 + fr, ks * 32 + fq * 8));
; #pragma unroll
;       for (int m = 1; m < 8; ++m) At[m] = *(const bf16x8*)(sa + lds_byte2(wr * 128 + m * 16 + fr, ks * 32 + fq * 8));
;       {
;         __builtin_amdgcn_sched_barrier(0);
;         if (t + 1 < nt) { G8_STAGE_R(cur ^ 1, Ab + (t + 1) * 64, Bb + (t + 1) * 64, 2 * ks, 2 * ks + 2); }
;         else if (has_next) { G8_STAGE_R(0, Abn, Bbn, 2 * ks, 2 * ks + 2); }
;         __builtin_amdgcn_sched_barrier(0);
;       }
; #pragma unroll
;       for (int m = 0; m < 8; ++m)
; #pragma unroll
;         for (int n = 0; n < 4; ++n) acc[m][n] = MFMA16(At[m], Bf[n], acc[m][n]);
.LBB0_1311:
	s_lshl_b32 s0, s74, 3
	s_add_i32 s0, s28, s0
	s_add_i32 s0, s0, s75
	s_lshl_b32 s1, s71, 3
	s_sub_i32 s0, s0, s1
	s_lshl_b32 s1, s0, 8
	s_mul_i32 s0, s0, 0x88000
	s_mul_hi_i32 s1, s1, 0x880
	s_add_u32 s0, s91, s0
	v_and_b32_e32 v198, 15, v8
	v_lshlrev_b64 v[178:179], 1, v[4:5]
	s_addc_u32 s1, s72, s1
	v_lshlrev_b64 v[180:181], 1, v[2:3]
	v_lshlrev_b64 v[194:195], 1, v[6:7]
	v_lshlrev_b64 v[196:197], 1, v[0:1]
	v_and_b32_e32 v206, 63, v8
	v_ashrrev_i32_e32 v10, 8, v8
	v_and_b32_e32 v204, 3, v9
	v_and_b32_e32 v9, 48, v8
	v_lshlrev_b32_e32 v199, 2, v198
	v_lshlrev_b32_e32 v8, 6, v8
	v_lshl_add_u64 v[130:131], s[0:1], 0, v[178:179]
	v_lshl_add_u64 v[132:133], s[0:1], 0, v[180:181]
	v_lshl_add_u64 v[134:135], s[0:1], 0, v[194:195]
	v_lshl_add_u64 v[136:137], s[0:1], 0, v[196:197]
	s_add_u32 s0, s57, s78
	v_lshlrev_b32_e32 v11, 6, v198
	v_and_b32_e32 v12, 32, v199
	v_lshlrev_b32_e32 v156, 14, v10
	v_and_b32_e32 v8, 0x3c0, v8
	s_addc_u32 s1, s58, s79
	v_lshlrev_b32_e32 v153, 13, v204
	v_bitop3_b32 v155, v11, v12, v9 bitop3:0x36
	v_lshlrev_b32_e32 v205, 7, v10
	v_or_b32_e32 v150, 0x800, v156
	v_bitop3_b32 v154, v8, v12, v9 bitop3:0x36
	v_or_b32_e32 v152, 0x1000, v156
	v_or_b32_e32 v151, 0x1800, v156
	v_or_b32_e32 v149, 0x2000, v156
	v_or_b32_e32 v148, 0x2800, v156
	v_or_b32_e32 v147, 0x3000, v156
	v_or_b32_e32 v146, 0x3800, v156
	v_lshl_add_u64 v[138:139], s[0:1], 0, v[178:179]
	v_lshl_add_u64 v[140:141], s[0:1], 0, v[180:181]
	v_lshl_add_u64 v[142:143], s[0:1], 0, v[194:195]
	v_lshl_add_u64 v[144:145], s[0:1], 0, v[196:197]
	s_mov_b64 s[0:1], 0
	s_mov_b32 s38, 0
	s_waitcnt vmcnt(8)
	s_mov_b32 s54, 0
	v_add3_u32 v0, s54, v155, v153
	v_add3_u32 v157, s54, v155, v156
	v_add3_u32 v238, s54, v154, v152
	v_add3_u32 v240, s54, v154, v149
	v_add3_u32 v242, s54, v154, v147
	v_add3_u32 v207, s54, v154, v150
	v_add3_u32 v239, s54, v154, v151
	v_add3_u32 v241, s54, v154, v148
	v_add3_u32 v243, s54, v154, v146
	ds_read_b128 v[158:161], v0 offset:32768
	ds_read_b128 v[162:165], v0 offset:34816
	ds_read_b128 v[174:177], v157
	ds_read_b128 v[186:189], v207
	ds_read_b128 v[190:193], v238
	ds_read_b128 v[212:215], v239
	ds_read_b128 v[222:225], v240
	ds_read_b128 v[226:229], v241
	ds_read_b128 v[230:233], v242
	ds_read_b128 v[234:237], v243
	ds_read_b128 v[166:169], v0 offset:36864
	ds_read_b128 v[170:173], v0 offset:38912
	s_and_b32 s39, s38, 0x10000
	s_xor_b32 s54, s39, 0x10000
	v_add_u32_e32 v244, s54, v185
	s_nop 0
	v_readfirstlane_b32 s39, v244
	s_waitcnt lgkmcnt(8)
	v_mfma_f32_16x16x32_bf16 v[126:129], v[174:177], v[158:161], 0
	v_mfma_f32_16x16x32_bf16 v[122:125], v[174:177], v[162:165], 0
	s_mov_b32 m0, s39
	v_lshl_add_u64 v[208:209], v[130:131], 0, s[0:1]
	global_load_lds_dwordx4 v[208:209], off
	v_mfma_f32_16x16x32_bf16 v[110:113], v[186:189], v[158:161], 0
	v_mfma_f32_16x16x32_bf16 v[106:109], v[186:189], v[162:165], 0
	s_add_u32 m0, s39, 0x8000
	v_lshl_add_u64 v[208:209], v[138:139], 0, s[0:1]
	global_load_lds_dwordx4 v[208:209], off
	s_waitcnt lgkmcnt(6)
	v_mfma_f32_16x16x32_bf16 v[94:97], v[190:193], v[158:161], 0
	v_mfma_f32_16x16x32_bf16 v[90:93], v[190:193], v[162:165], 0
	s_add_u32 m0, s39, 0x2000
	v_lshl_add_u64 v[208:209], v[132:133], 0, s[0:1]
	global_load_lds_dwordx4 v[208:209], off
	v_mfma_f32_16x16x32_bf16 v[78:81], v[212:215], v[158:161], 0
	v_mfma_f32_16x16x32_bf16 v[74:77], v[212:215], v[162:165], 0
	s_add_u32 m0, s39, 0xa000
	v_lshl_add_u64 v[208:209], v[140:141], 0, s[0:1]
	global_load_lds_dwordx4 v[208:209], off
	s_waitcnt lgkmcnt(4)
	v_mfma_f32_16x16x32_bf16 v[62:65], v[222:225], v[158:161], 0
	v_mfma_f32_16x16x32_bf16 v[58:61], v[222:225], v[162:165], 0
	s_add_u32 m0, s39, 0x4000
	v_lshl_add_u64 v[208:209], v[134:135], 0, s[0:1]
	global_load_lds_dwordx4 v[208:209], off
	v_mfma_f32_16x16x32_bf16 v[46:49], v[226:229], v[158:161], 0
	v_mfma_f32_16x16x32_bf16 v[42:45], v[226:229], v[162:165], 0
	s_add_u32 m0, s39, 0xc000
	v_lshl_add_u64 v[208:209], v[142:143], 0, s[0:1]
	global_load_lds_dwordx4 v[208:209], off
	s_waitcnt lgkmcnt(2)
	v_mfma_f32_16x16x32_bf16 v[30:33], v[230:233], v[158:161], 0
	v_mfma_f32_16x16x32_bf16 v[26:29], v[230:233], v[162:165], 0
	s_add_u32 m0, s39, 0x6000
	v_lshl_add_u64 v[208:209], v[136:137], 0, s[0:1]
	global_load_lds_dwordx4 v[208:209], off
	v_mfma_f32_16x16x32_bf16 v[14:17], v[234:237], v[158:161], 0
	v_mfma_f32_16x16x32_bf16 v[10:13], v[234:237], v[162:165], 0
	s_add_u32 m0, s39, 0xe000
	v_lshl_add_u64 v[208:209], v[144:145], 0, s[0:1]
	global_load_lds_dwordx4 v[208:209], off
	ds_read_b128 v[158:161], v0 offset:33792
	ds_read_b128 v[162:165], v0 offset:35840
	s_waitcnt lgkmcnt(2)
; #define MFMA16(a, b, c) __builtin_amdgcn_mfma_f32_16x16x32_bf16((a), (b), (c), 0, 0, 0)
; template <class Epi>
; DI void gemm8_tile(const bf16_t* __restrict__ Ab, int lda, const bf16_t* __restrict__ Bb, int ldb, int K, int brow, int bcol, const Epi epi,
;                    bool staged, bool has_next, const bf16_t* __restrict__ Abn, const bf16_t* __restrict__ Bbn) {
;     ...
; #pragma unroll
;     for (int ks = 0; ks < 2; ++ks) {
;       bf16x8 At[8], Bf[4];
;       Bf[0] = *(const bf16x8*)(sb + lds_byte2(wc * 64 + fr, ks * 32 + fq * 8));
;       At[0] = *(const bf16x8*)(sa + lds_byte2(wr * 128 + fr, ks * 32 + fq * 8));
; #pragma unroll
;       for (int n = 1; n < 4; ++n) Bf[n] = *(const bf16x8*)(sb + lds_byte2(wc * 64 + n * 16 + fr, ks * 32 + fq * 8));
; #pragma unroll
;       for (int m = 1; m < 8; ++m) At[m] = *(const bf16x8*)(sa + lds_byte2(wr * 128 + m * 16 + fr, ks * 32 + fq * 8));
;       {
;         __builtin_amdgcn_sched_barrier(0);
;         if (t + 1 < nt) { G8_STAGE_R(cur ^ 1, Ab + (t + 1) * 64, Bb + (t + 1) * 64, 2 * ks, 2 * ks + 2); }
;         else if (has_next) { G8_STAGE_R(0, Abn, Bbn, 2 * ks, 2 * ks + 2); }
;         __builtin_amdgcn_sched_barrier(0);
;       }
; #pragma unroll
;       for (int m = 0; m < 8; ++m)
; #pragma unroll
;         for (int n = 0; n < 4; ++n) acc[m][n] = MFMA16(At[m], Bf[n], acc[m][n]);
;       __builtin_amdgcn_sched_barrier(0);
;     }
;     asm volatile("s_waitcnt vmcnt(0)" ::: "memory");
;     __syncthreads();
	v_mfma_f32_16x16x32_bf16 v[118:121], v[174:177], v[166:169], 0
	v_mfma_f32_16x16x32_bf16 v[114:117], v[174:177], v[170:173], 0
	ds_read_b128 v[174:177], v157 offset:1024
	v_mfma_f32_16x16x32_bf16 v[102:105], v[186:189], v[166:169], 0
	v_mfma_f32_16x16x32_bf16 v[98:101], v[186:189], v[170:173], 0
	ds_read_b128 v[186:189], v207 offset:1024
	v_mfma_f32_16x16x32_bf16 v[86:89], v[190:193], v[166:169], 0
	v_mfma_f32_16x16x32_bf16 v[82:85], v[190:193], v[170:173], 0
	ds_read_b128 v[190:193], v238 offset:1024
	v_mfma_f32_16x16x32_bf16 v[70:73], v[212:215], v[166:169], 0
	v_mfma_f32_16x16x32_bf16 v[66:69], v[212:215], v[170:173], 0
	ds_read_b128 v[212:215], v239 offset:1024
	v_mfma_f32_16x16x32_bf16 v[54:57], v[222:225], v[166:169], 0
	v_mfma_f32_16x16x32_bf16 v[50:53], v[222:225], v[170:173], 0
	ds_read_b128 v[222:225], v240 offset:1024
	v_mfma_f32_16x16x32_bf16 v[38:41], v[226:229], v[166:169], 0
	v_mfma_f32_16x16x32_bf16 v[34:37], v[226:229], v[170:173], 0
	ds_read_b128 v[226:229], v241 offset:1024
	v_mfma_f32_16x16x32_bf16 v[22:25], v[230:233], v[166:169], 0
	v_mfma_f32_16x16x32_bf16 v[18:21], v[230:233], v[170:173], 0
	ds_read_b128 v[230:233], v242 offset:1024
	v_mfma_f32_16x16x32_bf16 v[6:9], v[234:237], v[166:169], 0
	v_mfma_f32_16x16x32_bf16 v[2:5], v[234:237], v[170:173], 0
	ds_read_b128 v[234:237], v243 offset:1024
	ds_read_b128 v[166:169], v0 offset:37888
	ds_read_b128 v[170:173], v0 offset:39936
	s_waitcnt lgkmcnt(8)
	v_mfma_f32_16x16x32_bf16 v[126:129], v[174:177], v[158:161], v[126:129]
	v_mfma_f32_16x16x32_bf16 v[122:125], v[174:177], v[162:165], v[122:125]
	v_add3_u32 v0, s54, v155, v153
	v_mfma_f32_16x16x32_bf16 v[110:113], v[186:189], v[158:161], v[110:113]
	v_mfma_f32_16x16x32_bf16 v[106:109], v[186:189], v[162:165], v[106:109]
	v_add3_u32 v157, s54, v155, v156
	s_waitcnt lgkmcnt(6)
	v_mfma_f32_16x16x32_bf16 v[94:97], v[190:193], v[158:161], v[94:97]
	v_mfma_f32_16x16x32_bf16 v[90:93], v[190:193], v[162:165], v[90:93]
	v_add3_u32 v238, s54, v154, v152
	v_mfma_f32_16x16x32_bf16 v[78:81], v[212:215], v[158:161], v[78:81]
	v_mfma_f32_16x16x32_bf16 v[74:77], v[212:215], v[162:165], v[74:77]
	v_add3_u32 v240, s54, v154, v149
	s_waitcnt lgkmcnt(4)
	v_mfma_f32_16x16x32_bf16 v[62:65], v[222:225], v[158:161], v[62:65]
	v_mfma_f32_16x16x32_bf16 v[58:61], v[222:225], v[162:165], v[58:61]
	v_add3_u32 v242, s54, v154, v147
	v_mfma_f32_16x16x32_bf16 v[46:49], v[226:229], v[158:161], v[46:49]
	v_mfma_f32_16x16x32_bf16 v[42:45], v[226:229], v[162:165], v[42:45]
	v_add3_u32 v207, s54, v154, v150
	s_waitcnt lgkmcnt(2)
	v_mfma_f32_16x16x32_bf16 v[30:33], v[230:233], v[158:161], v[30:33]
	v_mfma_f32_16x16x32_bf16 v[26:29], v[230:233], v[162:165], v[26:29]
	v_add3_u32 v239, s54, v154, v151
	v_mfma_f32_16x16x32_bf16 v[14:17], v[234:237], v[158:161], v[14:17]
	v_mfma_f32_16x16x32_bf16 v[10:13], v[234:237], v[162:165], v[10:13]
	v_add3_u32 v241, s54, v154, v148
	v_add3_u32 v243, s54, v154, v146
	s_waitcnt vmcnt(0) lgkmcnt(0)
	s_barrier
	ds_read_b128 v[158:161], v0 offset:32768
	ds_read_b128 v[162:165], v0 offset:34816
	v_mfma_f32_16x16x32_bf16 v[118:121], v[174:177], v[166:169], v[118:121]
	v_mfma_f32_16x16x32_bf16 v[114:117], v[174:177], v[170:173], v[114:117]
	ds_read_b128 v[174:177], v157
	v_mfma_f32_16x16x32_bf16 v[102:105], v[186:189], v[166:169], v[102:105]
	v_mfma_f32_16x16x32_bf16 v[98:101], v[186:189], v[170:173], v[98:101]
	ds_read_b128 v[186:189], v207
	v_mfma_f32_16x16x32_bf16 v[86:89], v[190:193], v[166:169], v[86:89]
	v_mfma_f32_16x16x32_bf16 v[82:85], v[190:193], v[170:173], v[82:85]
	ds_read_b128 v[190:193], v238
	v_mfma_f32_16x16x32_bf16 v[70:73], v[212:215], v[166:169], v[70:73]
	v_mfma_f32_16x16x32_bf16 v[66:69], v[212:215], v[170:173], v[66:69]
	ds_read_b128 v[212:215], v239
	v_mfma_f32_16x16x32_bf16 v[54:57], v[222:225], v[166:169], v[54:57]
	v_mfma_f32_16x16x32_bf16 v[50:53], v[222:225], v[170:173], v[50:53]
	ds_read_b128 v[222:225], v240
	v_mfma_f32_16x16x32_bf16 v[38:41], v[226:229], v[166:169], v[38:41]
	v_mfma_f32_16x16x32_bf16 v[34:37], v[226:229], v[170:173], v[34:37]
	ds_read_b128 v[226:229], v241
	v_mfma_f32_16x16x32_bf16 v[22:25], v[230:233], v[166:169], v[22:25]
	v_mfma_f32_16x16x32_bf16 v[18:21], v[230:233], v[170:173], v[18:21]
	ds_read_b128 v[230:233], v242
	v_mfma_f32_16x16x32_bf16 v[6:9], v[234:237], v[166:169], v[6:9]
	v_mfma_f32_16x16x32_bf16 v[2:5], v[234:237], v[170:173], v[2:5]
	ds_read_b128 v[234:237], v243
	ds_read_b128 v[166:169], v0 offset:36864
	ds_read_b128 v[170:173], v0 offset:38912
	s_add_u32 s0, s0, 0x80
	s_addc_u32 s1, s1, 0
	s_add_i32 s38, s38, 0x10000

; #define MFMA16(a, b, c) __builtin_amdgcn_mfma_f32_16x16x32_bf16((a), (b), (c), 0, 0, 0)
; #define G8_STAGE(buf_, ap_, bp_) G8_STAGE_R(buf_, ap_, bp_, 0, 4)
; template <class Epi>
; DI void gemm8_tile(const bf16_t* __restrict__ Ab, int lda, const bf16_t* __restrict__ Bb, int ldb, int K, int brow, int bcol, const Epi epi,
;                    bool staged, bool has_next, const bf16_t* __restrict__ Abn, const bf16_t* __restrict__ Bbn) {
;     ...
;   for (int i = 0; i < 4; ++i) { int R, C; stage_rc2(wid * 1024 + i * 8192 + lane * 16, R, C); aoff[i] = (unsigned)R * (unsigned)lda + (unsigned)C; boff[i] = (unsigned)R * (unsigned)ldb + (unsigned)C; }
;     ...
;   f32x4 acc[8][4];
; #pragma unroll
;   for (int m = 0; m < 8; ++m)
; #pragma unroll
;     for (int n = 0; n < 4; ++n) acc[m][n] = (f32x4){0.f, 0.f, 0.f, 0.f};
;   const int nt = K / 64;
;   if (!staged) {
;     G8_STAGE(0, Ab, Bb);
;     asm volatile("s_waitcnt vmcnt(0)" ::: "memory");
;     __syncthreads();
;   }
;   for (int t = 0; t < nt; ++t) {
;     const int cur = t & 1;
;     const unsigned char* sa = smem + cur * G8_STAGE_B;
;     const unsigned char* sb = sa + G8_TILE_B;
; #pragma unroll
;     for (int ks = 0; ks < 2; ++ks) {
;       bf16x8 At[8], Bf[4];
;       Bf[0] = *(const bf16x8*)(sb + lds_byte2(wc * 64 + fr, ks * 32 + fq * 8));
;       At[0] = *(const bf16x8*)(sa + lds_byte2(wr * 128 + fr, ks * 32 + fq * 8));
; #pragma unroll
;       for (int n = 1; n < 4; ++n) Bf[n] = *(const bf16x8*)(sb + lds_byte2(wc * 64 + n * 16 + fr, ks * 32 + fq * 8));
; #pragma unroll
;       for (int m = 1; m < 8; ++m) At[m] = *(const bf16x8*)(sa + lds_byte2(wr * 128 + m * 16 + fr, ks * 32 + fq * 8));
;       {
;         __builtin_amdgcn_sched_barrier(0);
;         if (t + 1 < nt) { G8_STAGE_R(cur ^ 1, Ab + (t + 1) * 64, Bb + (t + 1) * 64, 2 * ks, 2 * ks + 2); }
;         else if (has_next) { G8_STAGE_R(0, Abn, Bbn, 2 * ks, 2 * ks + 2); }
;         __builtin_amdgcn_sched_barrier(0);
;       }
; #pragma unroll
;       for (int m = 0; m < 8; ++m)
; #pragma unroll
;         for (int n = 0; n < 4; ++n) acc[m][n] = MFMA16(At[m], Bf[n], acc[m][n]);
.LBB0_1509:
	s_lshl_b32 s14, s75, 3
	s_add_i32 s14, s28, s14
	s_add_i32 s14, s14, s78
	s_lshl_b32 s15, s74, 3
	s_sub_i32 s14, s14, s15
	s_lshl_b32 s15, s14, 8
	s_add_u32 s0, s91, s0
	s_mul_i32 s14, s14, 0x88000
	s_addc_u32 s1, s72, s1
	v_and_b32_e32 v200, 15, v2
	s_mul_hi_i32 s15, s15, 0x880
	s_add_u32 s0, s0, s14
	v_and_b32_e32 v208, 63, v2
	v_ashrrev_i32_e32 v4, 8, v2
	v_and_b32_e32 v206, 3, v3
	v_and_b32_e32 v3, 48, v2
	v_lshlrev_b32_e32 v201, 2, v200
	v_lshlrev_b32_e32 v2, 6, v2
	s_addc_u32 s1, s1, s15
	v_and_b32_e32 v6, 32, v201
	v_and_b32_e32 v2, 0x3c0, v2
	v_lshl_add_u64 v[130:131], v[178:179], 1, s[0:1]
	v_lshl_add_u64 v[132:133], v[182:183], 1, s[0:1]
	v_lshl_add_u64 v[134:135], v[194:195], 1, s[0:1]
	v_lshl_add_u64 v[136:137], v[198:199], 1, s[0:1]
	s_add_u32 s0, s59, s9
	v_lshlrev_b32_e32 v5, 6, v200
	v_lshlrev_b32_e32 v156, 14, v4
	v_bitop3_b32 v154, v2, v6, v3 bitop3:0x36
	s_addc_u32 s1, s70, s79
	v_lshlrev_b32_e32 v153, 13, v206
	v_bitop3_b32 v155, v5, v6, v3 bitop3:0x36
	v_lshlrev_b32_e32 v207, 7, v4
	v_or_b32_e32 v150, 0x800, v156
	v_or_b32_e32 v152, 0x1000, v156
	v_or_b32_e32 v151, 0x1800, v156
	v_or_b32_e32 v149, 0x2000, v156
	v_or_b32_e32 v148, 0x2800, v156
	v_or_b32_e32 v147, 0x3000, v156
	v_or_b32_e32 v146, 0x3800, v156
	v_lshl_add_u64 v[138:139], v[180:181], 1, s[0:1]
	v_lshl_add_u64 v[140:141], v[184:185], 1, s[0:1]
	v_lshl_add_u64 v[142:143], v[196:197], 1, s[0:1]
	v_lshl_add_u64 v[144:145], v[0:1], 1, s[0:1]
	s_mov_b64 s[0:1], 0
	s_mov_b32 s9, 0
	s_waitcnt vmcnt(8)
	s_mov_b32 s15, 0
	v_add3_u32 v157, s15, v155, v153
	v_add3_u32 v209, s15, v155, v156
	v_add3_u32 v245, s15, v154, v152
	v_add3_u32 v247, s15, v154, v149
	v_add3_u32 v249, s15, v154, v147
	v_add3_u32 v244, s15, v154, v150
	v_add3_u32 v246, s15, v154, v151
	v_add3_u32 v248, s15, v154, v148
	v_add3_u32 v250, s15, v154, v146
	ds_read_b128 v[158:161], v157 offset:32768
	ds_read_b128 v[162:165], v157 offset:34816
	ds_read_b128 v[174:177], v209
	ds_read_b128 v[190:193], v244
	ds_read_b128 v[212:215], v245
	ds_read_b128 v[222:225], v246
	ds_read_b128 v[226:229], v247
	ds_read_b128 v[230:233], v248
	ds_read_b128 v[234:237], v249
	ds_read_b128 v[238:241], v250
	ds_read_b128 v[166:169], v157 offset:36864
	ds_read_b128 v[170:173], v157 offset:38912
	s_and_b32 s14, s9, 0x10000
	s_xor_b32 s15, s14, 0x10000
	v_add_u32_e32 v251, s15, v189
	s_nop 0
	v_readfirstlane_b32 s14, v251
	s_waitcnt lgkmcnt(8)
	v_mfma_f32_16x16x32_bf16 v[126:129], v[174:177], v[158:161], 0
	v_mfma_f32_16x16x32_bf16 v[122:125], v[174:177], v[162:165], 0
	s_mov_b32 m0, s14
	v_lshl_add_u64 v[242:243], v[130:131], 0, s[0:1]
	global_load_lds_dwordx4 v[242:243], off
	v_mfma_f32_16x16x32_bf16 v[110:113], v[190:193], v[158:161], 0
	v_mfma_f32_16x16x32_bf16 v[106:109], v[190:193], v[162:165], 0
	s_add_u32 m0, s14, 0x8000
	v_lshl_add_u64 v[242:243], v[138:139], 0, s[0:1]
	global_load_lds_dwordx4 v[242:243], off
	s_waitcnt lgkmcnt(6)
	v_mfma_f32_16x16x32_bf16 v[94:97], v[212:215], v[158:161], 0
	v_mfma_f32_16x16x32_bf16 v[90:93], v[212:215], v[162:165], 0
	s_add_u32 m0, s14, 0x2000
	v_lshl_add_u64 v[242:243], v[132:133], 0, s[0:1]
	global_load_lds_dwordx4 v[242:243], off
	v_mfma_f32_16x16x32_bf16 v[78:81], v[222:225], v[158:161], 0
	v_mfma_f32_16x16x32_bf16 v[74:77], v[222:225], v[162:165], 0
	s_add_u32 m0, s14, 0xa000
	v_lshl_add_u64 v[242:243], v[140:141], 0, s[0:1]
	global_load_lds_dwordx4 v[242:243], off
	s_waitcnt lgkmcnt(4)
	v_mfma_f32_16x16x32_bf16 v[62:65], v[226:229], v[158:161], 0
	v_mfma_f32_16x16x32_bf16 v[58:61], v[226:229], v[162:165], 0
	s_add_u32 m0, s14, 0x4000
	v_lshl_add_u64 v[242:243], v[134:135], 0, s[0:1]
	global_load_lds_dwordx4 v[242:243], off
	v_mfma_f32_16x16x32_bf16 v[46:49], v[230:233], v[158:161], 0
	v_mfma_f32_16x16x32_bf16 v[42:45], v[230:233], v[162:165], 0
	s_add_u32 m0, s14, 0xc000
	v_lshl_add_u64 v[242:243], v[142:143], 0, s[0:1]
	global_load_lds_dwordx4 v[242:243], off
	s_waitcnt lgkmcnt(2)
	v_mfma_f32_16x16x32_bf16 v[30:33], v[234:237], v[158:161], 0
	v_mfma_f32_16x16x32_bf16 v[26:29], v[234:237], v[162:165], 0
	s_add_u32 m0, s14, 0x6000
	v_lshl_add_u64 v[242:243], v[136:137], 0, s[0:1]
	global_load_lds_dwordx4 v[242:243], off
	v_mfma_f32_16x16x32_bf16 v[14:17], v[238:241], v[158:161], 0
	v_mfma_f32_16x16x32_bf16 v[10:13], v[238:241], v[162:165], 0
	s_add_u32 m0, s14, 0xe000
	v_lshl_add_u64 v[242:243], v[144:145], 0, s[0:1]
	global_load_lds_dwordx4 v[242:243], off
	ds_read_b128 v[158:161], v157 offset:33792
	ds_read_b128 v[162:165], v157 offset:35840
	s_waitcnt lgkmcnt(2)
; #define MFMA16(a, b, c) __builtin_amdgcn_mfma_f32_16x16x32_bf16((a), (b), (c), 0, 0, 0)
; template <class Epi>
; DI void gemm8_tile(const bf16_t* __restrict__ Ab, int lda, const bf16_t* __restrict__ Bb, int ldb, int K, int brow, int bcol, const Epi epi,
;                    bool staged, bool has_next, const bf16_t* __restrict__ Abn, const bf16_t* __restrict__ Bbn) {
;     ...
; #pragma unroll
;     for (int ks = 0; ks < 2; ++ks) {
;       bf16x8 At[8], Bf[4];
;       Bf[0] = *(const bf16x8*)(sb + lds_byte2(wc * 64 + fr, ks * 32 + fq * 8));
;       At[0] = *(const bf16x8*)(sa + lds_byte2(wr * 128 + fr, ks * 32 + fq * 8));
; #pragma unroll
;       for (int n = 1; n < 4; ++n) Bf[n] = *(const bf16x8*)(sb + lds_byte2(wc * 64 + n * 16 + fr, ks * 32 + fq * 8));
; #pragma unroll
;       for (int m = 1; m < 8; ++m) At[m] = *(const bf16x8*)(sa + lds_byte2(wr * 128 + m * 16 + fr, ks * 32 + fq * 8));
;       {
;         __builtin_amdgcn_sched_barrier(0);
;         if (t + 1 < nt) { G8_STAGE_R(cur ^ 1, Ab + (t + 1) * 64, Bb + (t + 1) * 64, 2 * ks, 2 * ks + 2); }
;         else if (has_next) { G8_STAGE_R(0, Abn, Bbn, 2 * ks, 2 * ks + 2); }
;         __builtin_amdgcn_sched_barrier(0);
;       }
; #pragma unroll
;       for (int m = 0; m < 8; ++m)
; #pragma unroll
;         for (int n = 0; n < 4; ++n) acc[m][n] = MFMA16(At[m], Bf[n], acc[m][n]);
;       __builtin_amdgcn_sched_barrier(0);
;     }
;     asm volatile("s_waitcnt vmcnt(0)" ::: "memory");
;     __syncthreads();
	v_mfma_f32_16x16x32_bf16 v[118:121], v[174:177], v[166:169], 0
	v_mfma_f32_16x16x32_bf16 v[114:117], v[174:177], v[170:173], 0
	ds_read_b128 v[174:177], v209 offset:1024
	v_mfma_f32_16x16x32_bf16 v[102:105], v[190:193], v[166:169], 0
	v_mfma_f32_16x16x32_bf16 v[98:101], v[190:193], v[170:173], 0
	ds_read_b128 v[190:193], v244 offset:1024
	v_mfma_f32_16x16x32_bf16 v[86:89], v[212:215], v[166:169], 0
	v_mfma_f32_16x16x32_bf16 v[82:85], v[212:215], v[170:173], 0
	ds_read_b128 v[212:215], v245 offset:1024
	v_mfma_f32_16x16x32_bf16 v[70:73], v[222:225], v[166:169], 0
	v_mfma_f32_16x16x32_bf16 v[66:69], v[222:225], v[170:173], 0
	ds_read_b128 v[222:225], v246 offset:1024
	v_mfma_f32_16x16x32_bf16 v[54:57], v[226:229], v[166:169], 0
	v_mfma_f32_16x16x32_bf16 v[50:53], v[226:229], v[170:173], 0
	ds_read_b128 v[226:229], v247 offset:1024
	v_mfma_f32_16x16x32_bf16 v[38:41], v[230:233], v[166:169], 0
	v_mfma_f32_16x16x32_bf16 v[34:37], v[230:233], v[170:173], 0
	ds_read_b128 v[230:233], v248 offset:1024
	v_mfma_f32_16x16x32_bf16 v[22:25], v[234:237], v[166:169], 0
	v_mfma_f32_16x16x32_bf16 v[18:21], v[234:237], v[170:173], 0
	ds_read_b128 v[234:237], v249 offset:1024
	v_mfma_f32_16x16x32_bf16 v[6:9], v[238:241], v[166:169], 0
	v_mfma_f32_16x16x32_bf16 v[2:5], v[238:241], v[170:173], 0
	ds_read_b128 v[238:241], v250 offset:1024
	ds_read_b128 v[166:169], v157 offset:37888
	ds_read_b128 v[170:173], v157 offset:39936
	s_waitcnt lgkmcnt(8)
	v_mfma_f32_16x16x32_bf16 v[126:129], v[174:177], v[158:161], v[126:129]
	v_mfma_f32_16x16x32_bf16 v[122:125], v[174:177], v[162:165], v[122:125]
	v_add3_u32 v157, s15, v155, v153
	v_mfma_f32_16x16x32_bf16 v[110:113], v[190:193], v[158:161], v[110:113]
	v_mfma_f32_16x16x32_bf16 v[106:109], v[190:193], v[162:165], v[106:109]
	v_add3_u32 v209, s15, v155, v156
	s_waitcnt lgkmcnt(6)
	v_mfma_f32_16x16x32_bf16 v[94:97], v[212:215], v[158:161], v[94:97]
	v_mfma_f32_16x16x32_bf16 v[90:93], v[212:215], v[162:165], v[90:93]
	v_add3_u32 v245, s15, v154, v152
	v_mfma_f32_16x16x32_bf16 v[78:81], v[222:225], v[158:161], v[78:81]
	v_mfma_f32_16x16x32_bf16 v[74:77], v[222:225], v[162:165], v[74:77]
	v_add3_u32 v247, s15, v154, v149
	s_waitcnt lgkmcnt(4)
	v_mfma_f32_16x16x32_bf16 v[62:65], v[226:229], v[158:161], v[62:65]
	v_mfma_f32_16x16x32_bf16 v[58:61], v[226:229], v[162:165], v[58:61]
	v_add3_u32 v249, s15, v154, v147
	v_mfma_f32_16x16x32_bf16 v[46:49], v[230:233], v[158:161], v[46:49]
	v_mfma_f32_16x16x32_bf16 v[42:45], v[230:233], v[162:165], v[42:45]
	v_add3_u32 v244, s15, v154, v150
	s_waitcnt lgkmcnt(2)
	v_mfma_f32_16x16x32_bf16 v[30:33], v[234:237], v[158:161], v[30:33]
	v_mfma_f32_16x16x32_bf16 v[26:29], v[234:237], v[162:165], v[26:29]
	v_add3_u32 v246, s15, v154, v151
	v_mfma_f32_16x16x32_bf16 v[14:17], v[238:241], v[158:161], v[14:17]
	v_mfma_f32_16x16x32_bf16 v[10:13], v[238:241], v[162:165], v[10:13]
	v_add3_u32 v248, s15, v154, v148
	v_add3_u32 v250, s15, v154, v146
	s_waitcnt vmcnt(0) lgkmcnt(0)
	s_barrier
	ds_read_b128 v[158:161], v157 offset:32768
	ds_read_b128 v[162:165], v157 offset:34816
	v_mfma_f32_16x16x32_bf16 v[118:121], v[174:177], v[166:169], v[118:121]
	v_mfma_f32_16x16x32_bf16 v[114:117], v[174:177], v[170:173], v[114:117]
	ds_read_b128 v[174:177], v209
	v_mfma_f32_16x16x32_bf16 v[102:105], v[190:193], v[166:169], v[102:105]
	v_mfma_f32_16x16x32_bf16 v[98:101], v[190:193], v[170:173], v[98:101]
	ds_read_b128 v[190:193], v244
	v_mfma_f32_16x16x32_bf16 v[86:89], v[212:215], v[166:169], v[86:89]
	v_mfma_f32_16x16x32_bf16 v[82:85], v[212:215], v[170:173], v[82:85]
	ds_read_b128 v[212:215], v245
	v_mfma_f32_16x16x32_bf16 v[70:73], v[222:225], v[166:169], v[70:73]
	v_mfma_f32_16x16x32_bf16 v[66:69], v[222:225], v[170:173], v[66:69]
	ds_read_b128 v[222:225], v246
	v_mfma_f32_16x16x32_bf16 v[54:57], v[226:229], v[166:169], v[54:57]
	v_mfma_f32_16x16x32_bf16 v[50:53], v[226:229], v[170:173], v[50:53]
	ds_read_b128 v[226:229], v247
	v_mfma_f32_16x16x32_bf16 v[38:41], v[230:233], v[166:169], v[38:41]
	v_mfma_f32_16x16x32_bf16 v[34:37], v[230:233], v[170:173], v[34:37]
	ds_read_b128 v[230:233], v248
	v_mfma_f32_16x16x32_bf16 v[22:25], v[234:237], v[166:169], v[22:25]
	v_mfma_f32_16x16x32_bf16 v[18:21], v[234:237], v[170:173], v[18:21]
	ds_read_b128 v[234:237], v249
	v_mfma_f32_16x16x32_bf16 v[6:9], v[238:241], v[166:169], v[6:9]
	v_mfma_f32_16x16x32_bf16 v[2:5], v[238:241], v[170:173], v[2:5]
	ds_read_b128 v[238:241], v250
	ds_read_b128 v[166:169], v157 offset:36864
	ds_read_b128 v[170:173], v157 offset:38912
	s_add_u32 s0, s0, 0x80
	s_addc_u32 s1, s1, 0
	s_add_i32 s9, s9, 0x10000

; #define MFMA16(a, b, c) __builtin_amdgcn_mfma_f32_16x16x32_bf16((a), (b), (c), 0, 0, 0)
; #define G8_STAGE(buf_, ap_, bp_) G8_STAGE_R(buf_, ap_, bp_, 0, 4)
; template <class Epi>
; DI void gemm8_tile(const bf16_t* __restrict__ Ab, int lda, const bf16_t* __restrict__ Bb, int ldb, int K, int brow, int bcol, const Epi epi,
;                    bool staged, bool has_next, const bf16_t* __restrict__ Abn, const bf16_t* __restrict__ Bbn) {
;     ...
;   for (int i = 0; i < 4; ++i) { int R, C; stage_rc2(wid * 1024 + i * 8192 + lane * 16, R, C); aoff[i] = (unsigned)R * (unsigned)lda + (unsigned)C; boff[i] = (unsigned)R * (unsigned)ldb + (unsigned)C; }
;     ...
;   f32x4 acc[8][4];
; #pragma unroll
;   for (int m = 0; m < 8; ++m)
; #pragma unroll
;     for (int n = 0; n < 4; ++n) acc[m][n] = (f32x4){0.f, 0.f, 0.f, 0.f};
;   const int nt = K / 64;
;   if (!staged) {
;     G8_STAGE(0, Ab, Bb);
;     asm volatile("s_waitcnt vmcnt(0)" ::: "memory");
;     __syncthreads();
;   }
;   for (int t = 0; t < nt; ++t) {
;     const int cur = t & 1;
;     const unsigned char* sa = smem + cur * G8_STAGE_B;
;     const unsigned char* sb = sa + G8_TILE_B;
; #pragma unroll
;     for (int ks = 0; ks < 2; ++ks) {
;       bf16x8 At[8], Bf[4];
;       Bf[0] = *(const bf16x8*)(sb + lds_byte2(wc * 64 + fr, ks * 32 + fq * 8));
;       At[0] = *(const bf16x8*)(sa + lds_byte2(wr * 128 + fr, ks * 32 + fq * 8));
; #pragma unroll
;       for (int n = 1; n < 4; ++n) Bf[n] = *(const bf16x8*)(sb + lds_byte2(wc * 64 + n * 16 + fr, ks * 32 + fq * 8));
; #pragma unroll
;       for (int m = 1; m < 8; ++m) At[m] = *(const bf16x8*)(sa + lds_byte2(wr * 128 + m * 16 + fr, ks * 32 + fq * 8));
;       {
;         __builtin_amdgcn_sched_barrier(0);
;         if (t + 1 < nt) { G8_STAGE_R(cur ^ 1, Ab + (t + 1) * 64, Bb + (t + 1) * 64, 2 * ks, 2 * ks + 2); }
;         else if (has_next) { G8_STAGE_R(0, Abn, Bbn, 2 * ks, 2 * ks + 2); }
;         __builtin_amdgcn_sched_barrier(0);
;       }
; #pragma unroll
;       for (int m = 0; m < 8; ++m)
; #pragma unroll
;         for (int n = 0; n < 4; ++n) acc[m][n] = MFMA16(At[m], Bf[n], acc[m][n]);
.LBB0_1672:
	v_readlane_b32 s0, v253, 23
	s_add_u32 s0, s0, s57
	v_readlane_b32 s1, v253, 24
	v_lshlrev_b64 v[212:213], 1, v[0:1]
	s_addc_u32 s1, s1, s58
	v_lshlrev_b64 v[214:215], 1, v[6:7]
	v_lshlrev_b64 v[146:147], 1, v[4:5]
	v_lshlrev_b64 v[148:149], 1, v[2:3]
	v_lshl_add_u64 v[130:131], s[0:1], 0, v[212:213]
	v_lshl_add_u64 v[132:133], s[0:1], 0, v[214:215]
	v_lshl_add_u64 v[134:135], s[0:1], 0, v[146:147]
	v_lshl_add_u64 v[136:137], s[0:1], 0, v[148:149]
	s_lshl_b32 s0, s55, 3
	s_add_i32 s0, s28, s0
	s_add_i32 s0, s0, s56
	s_lshl_b32 s1, s54, 3
	s_sub_i32 s0, s0, s1
	s_lshl_b32 s1, s0, 8
	s_mul_i32 s0, s0, 0x88000
	v_readlane_b32 s4, v253, 6
	v_and_b32_e32 v228, 63, v8
	v_and_b32_e32 v229, 3, v9
	v_ashrrev_i32_e32 v9, 8, v8
	v_and_b32_e32 v223, 15, v8
	v_and_b32_e32 v10, 48, v8
	v_lshlrev_b32_e32 v12, 2, v8
	v_lshlrev_b32_e32 v8, 6, v8
	s_mul_hi_i32 s1, s1, 0x880
	s_add_u32 s0, s4, s0
	v_readlane_b32 s4, v253, 7
	v_lshlrev_b32_e32 v11, 6, v223
	v_and_b32_e32 v12, 32, v12
	v_lshlrev_b32_e32 v158, 14, v9
	v_and_b32_e32 v8, 0x3c0, v8
	s_addc_u32 s1, s4, s1
	v_lshlrev_b32_e32 v151, 13, v229
	v_bitop3_b32 v153, v11, v12, v10 bitop3:0x36
	v_lshlrev_b32_e32 v230, 7, v9
	v_or_b32_e32 v150, 0x800, v158
	v_bitop3_b32 v152, v8, v12, v10 bitop3:0x36
	v_or_b32_e32 v167, 0x1000, v158
	v_or_b32_e32 v166, 0x1800, v158
	v_or_b32_e32 v165, 0x2000, v158
	v_or_b32_e32 v164, 0x2800, v158
	v_or_b32_e32 v163, 0x3000, v158
	v_or_b32_e32 v162, 0x3800, v158
	v_lshl_add_u64 v[138:139], s[0:1], 0, v[212:213]
	v_lshl_add_u64 v[140:141], s[0:1], 0, v[214:215]
	v_lshl_add_u64 v[142:143], s[0:1], 0, v[146:147]
	v_lshl_add_u64 v[144:145], s[0:1], 0, v[148:149]
	s_mov_b64 s[0:1], 0
	s_mov_b32 s14, 0
	s_waitcnt vmcnt(8)
	s_mov_b32 s38, 0
	v_add3_u32 v0, s38, v153, v151
	v_add3_u32 v159, s38, v153, v158
	v_add3_u32 v209, s38, v152, v167
	v_add3_u32 v240, s38, v152, v165
	v_add3_u32 v242, s38, v152, v163
	v_add3_u32 v208, s38, v152, v150
	v_add3_u32 v231, s38, v152, v166
	v_add3_u32 v241, s38, v152, v164
	v_add3_u32 v243, s38, v152, v162
	ds_read_b128 v[168:171], v0 offset:32768
	ds_read_b128 v[172:175], v0 offset:34816
	ds_read_b128 v[184:187], v159
	ds_read_b128 v[188:191], v208
	ds_read_b128 v[192:195], v209
	ds_read_b128 v[196:199], v231
	ds_read_b128 v[200:203], v240
	ds_read_b128 v[204:207], v241
	ds_read_b128 v[232:235], v242
	ds_read_b128 v[236:239], v243
	ds_read_b128 v[176:179], v0 offset:36864
	ds_read_b128 v[180:183], v0 offset:38912
	s_and_b32 s15, s14, 0x10000
	s_xor_b32 s38, s15, 0x10000
	v_add_u32_e32 v244, s38, v157
	s_nop 0
	v_readfirstlane_b32 s15, v244
	s_waitcnt lgkmcnt(8)
	v_mfma_f32_16x16x32_bf16 v[126:129], v[184:187], v[168:171], 0
	v_mfma_f32_16x16x32_bf16 v[122:125], v[184:187], v[172:175], 0
	s_mov_b32 m0, s15
	v_lshl_add_u64 v[160:161], v[144:145], 0, s[0:1]
	global_load_lds_dwordx4 v[160:161], off
	v_mfma_f32_16x16x32_bf16 v[110:113], v[188:191], v[168:171], 0
	v_mfma_f32_16x16x32_bf16 v[106:109], v[188:191], v[172:175], 0
	s_add_u32 m0, s15, 0x8000
	v_lshl_add_u64 v[160:161], v[136:137], 0, s[0:1]
	global_load_lds_dwordx4 v[160:161], off
	s_waitcnt lgkmcnt(6)
	v_mfma_f32_16x16x32_bf16 v[94:97], v[192:195], v[168:171], 0
	v_mfma_f32_16x16x32_bf16 v[90:93], v[192:195], v[172:175], 0
	s_add_u32 m0, s15, 0x2000
	v_lshl_add_u64 v[160:161], v[142:143], 0, s[0:1]
	global_load_lds_dwordx4 v[160:161], off
	v_mfma_f32_16x16x32_bf16 v[78:81], v[196:199], v[168:171], 0
	v_mfma_f32_16x16x32_bf16 v[74:77], v[196:199], v[172:175], 0
	s_add_u32 m0, s15, 0xa000
	v_lshl_add_u64 v[160:161], v[134:135], 0, s[0:1]
	global_load_lds_dwordx4 v[160:161], off
	s_waitcnt lgkmcnt(4)
	v_mfma_f32_16x16x32_bf16 v[62:65], v[200:203], v[168:171], 0
	v_mfma_f32_16x16x32_bf16 v[58:61], v[200:203], v[172:175], 0
	s_add_u32 m0, s15, 0x4000
	v_lshl_add_u64 v[160:161], v[140:141], 0, s[0:1]
	global_load_lds_dwordx4 v[160:161], off
	v_mfma_f32_16x16x32_bf16 v[46:49], v[204:207], v[168:171], 0
	v_mfma_f32_16x16x32_bf16 v[42:45], v[204:207], v[172:175], 0
	s_add_u32 m0, s15, 0xc000
	v_lshl_add_u64 v[160:161], v[132:133], 0, s[0:1]
	global_load_lds_dwordx4 v[160:161], off
	s_waitcnt lgkmcnt(2)
	v_mfma_f32_16x16x32_bf16 v[30:33], v[232:235], v[168:171], 0
	v_mfma_f32_16x16x32_bf16 v[26:29], v[232:235], v[172:175], 0
	s_add_u32 m0, s15, 0x6000
	v_lshl_add_u64 v[160:161], v[138:139], 0, s[0:1]
	global_load_lds_dwordx4 v[160:161], off
	v_mfma_f32_16x16x32_bf16 v[14:17], v[236:239], v[168:171], 0
	v_mfma_f32_16x16x32_bf16 v[10:13], v[236:239], v[172:175], 0
	s_add_u32 m0, s15, 0xe000
	v_lshl_add_u64 v[160:161], v[130:131], 0, s[0:1]
	global_load_lds_dwordx4 v[160:161], off
	ds_read_b128 v[168:171], v0 offset:33792
	ds_read_b128 v[172:175], v0 offset:35840
	s_waitcnt lgkmcnt(2)
; #define MFMA16(a, b, c) __builtin_amdgcn_mfma_f32_16x16x32_bf16((a), (b), (c), 0, 0, 0)
; template <class Epi>
; DI void gemm8_tile(const bf16_t* __restrict__ Ab, int lda, const bf16_t* __restrict__ Bb, int ldb, int K, int brow, int bcol, const Epi epi,
;                    bool staged, bool has_next, const bf16_t* __restrict__ Abn, const bf16_t* __restrict__ Bbn) {
;     ...
; #pragma unroll
;     for (int ks = 0; ks < 2; ++ks) {
;       bf16x8 At[8], Bf[4];
;       Bf[0] = *(const bf16x8*)(sb + lds_byte2(wc * 64 + fr, ks * 32 + fq * 8));
;       At[0] = *(const bf16x8*)(sa + lds_byte2(wr * 128 + fr, ks * 32 + fq * 8));
; #pragma unroll
;       for (int n = 1; n < 4; ++n) Bf[n] = *(const bf16x8*)(sb + lds_byte2(wc * 64 + n * 16 + fr, ks * 32 + fq * 8));
; #pragma unroll
;       for (int m = 1; m < 8; ++m) At[m] = *(const bf16x8*)(sa + lds_byte2(wr * 128 + m * 16 + fr, ks * 32 + fq * 8));
;       {
;         __builtin_amdgcn_sched_barrier(0);
;         if (t + 1 < nt) { G8_STAGE_R(cur ^ 1, Ab + (t + 1) * 64, Bb + (t + 1) * 64, 2 * ks, 2 * ks + 2); }
;         else if (has_next) { G8_STAGE_R(0, Abn, Bbn, 2 * ks, 2 * ks + 2); }
;         __builtin_amdgcn_sched_barrier(0);
;       }
; #pragma unroll
;       for (int m = 0; m < 8; ++m)
; #pragma unroll
;         for (int n = 0; n < 4; ++n) acc[m][n] = MFMA16(At[m], Bf[n], acc[m][n]);
;       __builtin_amdgcn_sched_barrier(0);
;     }
;     asm volatile("s_waitcnt vmcnt(0)" ::: "memory");
;     __syncthreads();
	v_mfma_f32_16x16x32_bf16 v[118:121], v[184:187], v[176:179], 0
	v_mfma_f32_16x16x32_bf16 v[114:117], v[184:187], v[180:183], 0
	ds_read_b128 v[184:187], v159 offset:1024
	v_mfma_f32_16x16x32_bf16 v[102:105], v[188:191], v[176:179], 0
	v_mfma_f32_16x16x32_bf16 v[98:101], v[188:191], v[180:183], 0
	ds_read_b128 v[188:191], v208 offset:1024
	v_mfma_f32_16x16x32_bf16 v[86:89], v[192:195], v[176:179], 0
	v_mfma_f32_16x16x32_bf16 v[82:85], v[192:195], v[180:183], 0
	ds_read_b128 v[192:195], v209 offset:1024
	v_mfma_f32_16x16x32_bf16 v[70:73], v[196:199], v[176:179], 0
	v_mfma_f32_16x16x32_bf16 v[66:69], v[196:199], v[180:183], 0
	ds_read_b128 v[196:199], v231 offset:1024
	v_mfma_f32_16x16x32_bf16 v[54:57], v[200:203], v[176:179], 0
	v_mfma_f32_16x16x32_bf16 v[50:53], v[200:203], v[180:183], 0
	ds_read_b128 v[200:203], v240 offset:1024
	v_mfma_f32_16x16x32_bf16 v[38:41], v[204:207], v[176:179], 0
	v_mfma_f32_16x16x32_bf16 v[34:37], v[204:207], v[180:183], 0
	ds_read_b128 v[204:207], v241 offset:1024
	v_mfma_f32_16x16x32_bf16 v[22:25], v[232:235], v[176:179], 0
	v_mfma_f32_16x16x32_bf16 v[18:21], v[232:235], v[180:183], 0
	ds_read_b128 v[232:235], v242 offset:1024
	v_mfma_f32_16x16x32_bf16 v[6:9], v[236:239], v[176:179], 0
	v_mfma_f32_16x16x32_bf16 v[2:5], v[236:239], v[180:183], 0
	ds_read_b128 v[236:239], v243 offset:1024
	ds_read_b128 v[176:179], v0 offset:37888
	ds_read_b128 v[180:183], v0 offset:39936
	s_waitcnt lgkmcnt(8)
	v_mfma_f32_16x16x32_bf16 v[126:129], v[184:187], v[168:171], v[126:129]
	v_mfma_f32_16x16x32_bf16 v[122:125], v[184:187], v[172:175], v[122:125]
	v_add3_u32 v0, s38, v153, v151
	v_mfma_f32_16x16x32_bf16 v[110:113], v[188:191], v[168:171], v[110:113]
	v_mfma_f32_16x16x32_bf16 v[106:109], v[188:191], v[172:175], v[106:109]
	v_add3_u32 v159, s38, v153, v158
	s_waitcnt lgkmcnt(6)
	v_mfma_f32_16x16x32_bf16 v[94:97], v[192:195], v[168:171], v[94:97]
	v_mfma_f32_16x16x32_bf16 v[90:93], v[192:195], v[172:175], v[90:93]
	v_add3_u32 v209, s38, v152, v167
	v_mfma_f32_16x16x32_bf16 v[78:81], v[196:199], v[168:171], v[78:81]
	v_mfma_f32_16x16x32_bf16 v[74:77], v[196:199], v[172:175], v[74:77]
	v_add3_u32 v240, s38, v152, v165
	s_waitcnt lgkmcnt(4)
	v_mfma_f32_16x16x32_bf16 v[62:65], v[200:203], v[168:171], v[62:65]
	v_mfma_f32_16x16x32_bf16 v[58:61], v[200:203], v[172:175], v[58:61]
	v_add3_u32 v242, s38, v152, v163
	v_mfma_f32_16x16x32_bf16 v[46:49], v[204:207], v[168:171], v[46:49]
	v_mfma_f32_16x16x32_bf16 v[42:45], v[204:207], v[172:175], v[42:45]
	v_add3_u32 v208, s38, v152, v150
	s_waitcnt lgkmcnt(2)
	v_mfma_f32_16x16x32_bf16 v[30:33], v[232:235], v[168:171], v[30:33]
	v_mfma_f32_16x16x32_bf16 v[26:29], v[232:235], v[172:175], v[26:29]
	v_add3_u32 v231, s38, v152, v166
	v_mfma_f32_16x16x32_bf16 v[14:17], v[236:239], v[168:171], v[14:17]
	v_mfma_f32_16x16x32_bf16 v[10:13], v[236:239], v[172:175], v[10:13]
	v_add3_u32 v241, s38, v152, v164
	v_add3_u32 v243, s38, v152, v162
	s_waitcnt vmcnt(0) lgkmcnt(0)
	s_barrier
	ds_read_b128 v[168:171], v0 offset:32768
	ds_read_b128 v[172:175], v0 offset:34816
	v_mfma_f32_16x16x32_bf16 v[118:121], v[184:187], v[176:179], v[118:121]
	v_mfma_f32_16x16x32_bf16 v[114:117], v[184:187], v[180:183], v[114:117]
	ds_read_b128 v[184:187], v159
	v_mfma_f32_16x16x32_bf16 v[102:105], v[188:191], v[176:179], v[102:105]
	v_mfma_f32_16x16x32_bf16 v[98:101], v[188:191], v[180:183], v[98:101]
	ds_read_b128 v[188:191], v208
	v_mfma_f32_16x16x32_bf16 v[86:89], v[192:195], v[176:179], v[86:89]
	v_mfma_f32_16x16x32_bf16 v[82:85], v[192:195], v[180:183], v[82:85]
	ds_read_b128 v[192:195], v209
	v_mfma_f32_16x16x32_bf16 v[70:73], v[196:199], v[176:179], v[70:73]
	v_mfma_f32_16x16x32_bf16 v[66:69], v[196:199], v[180:183], v[66:69]
	ds_read_b128 v[196:199], v231
	v_mfma_f32_16x16x32_bf16 v[54:57], v[200:203], v[176:179], v[54:57]
	v_mfma_f32_16x16x32_bf16 v[50:53], v[200:203], v[180:183], v[50:53]
	ds_read_b128 v[200:203], v240
	v_mfma_f32_16x16x32_bf16 v[38:41], v[204:207], v[176:179], v[38:41]
	v_mfma_f32_16x16x32_bf16 v[34:37], v[204:207], v[180:183], v[34:37]
	ds_read_b128 v[204:207], v241
	v_mfma_f32_16x16x32_bf16 v[22:25], v[232:235], v[176:179], v[22:25]
	v_mfma_f32_16x16x32_bf16 v[18:21], v[232:235], v[180:183], v[18:21]
	ds_read_b128 v[232:235], v242
	v_mfma_f32_16x16x32_bf16 v[6:9], v[236:239], v[176:179], v[6:9]
	v_mfma_f32_16x16x32_bf16 v[2:5], v[236:239], v[180:183], v[2:5]
	ds_read_b128 v[236:239], v243
	ds_read_b128 v[176:179], v0 offset:36864
	ds_read_b128 v[180:183], v0 offset:38912
	s_add_u32 s0, s0, 0x80
	s_addc_u32 s1, s1, 0
	s_add_i32 s14, s14, 0x10000

; #define MFMA16(a, b, c) __builtin_amdgcn_mfma_f32_16x16x32_bf16((a), (b), (c), 0, 0, 0)
; #define G8_STAGE(buf_, ap_, bp_) G8_STAGE_R(buf_, ap_, bp_, 0, 4)
; template <class Epi>
; DI void gemm8_tile(const bf16_t* __restrict__ Ab, int lda, const bf16_t* __restrict__ Bb, int ldb, int K, int brow, int bcol, const Epi epi,
;                    bool staged, bool has_next, const bf16_t* __restrict__ Abn, const bf16_t* __restrict__ Bbn) {
;     ...
;   for (int i = 0; i < 4; ++i) { int R, C; stage_rc2(wid * 1024 + i * 8192 + lane * 16, R, C); aoff[i] = (unsigned)R * (unsigned)lda + (unsigned)C; boff[i] = (unsigned)R * (unsigned)ldb + (unsigned)C; }
;     ...
;   f32x4 acc[8][4];
; #pragma unroll
;   for (int m = 0; m < 8; ++m)
; #pragma unroll
;     for (int n = 0; n < 4; ++n) acc[m][n] = (f32x4){0.f, 0.f, 0.f, 0.f};
;   const int nt = K / 64;
;   if (!staged) {
;     G8_STAGE(0, Ab, Bb);
;     asm volatile("s_waitcnt vmcnt(0)" ::: "memory");
;     __syncthreads();
;   }
;   for (int t = 0; t < nt; ++t) {
;     const int cur = t & 1;
;     const unsigned char* sa = smem + cur * G8_STAGE_B;
;     const unsigned char* sb = sa + G8_TILE_B;
; #pragma unroll
;     for (int ks = 0; ks < 2; ++ks) {
;       bf16x8 At[8], Bf[4];
;       Bf[0] = *(const bf16x8*)(sb + lds_byte2(wc * 64 + fr, ks * 32 + fq * 8));
;       At[0] = *(const bf16x8*)(sa + lds_byte2(wr * 128 + fr, ks * 32 + fq * 8));
; #pragma unroll
;       for (int n = 1; n < 4; ++n) Bf[n] = *(const bf16x8*)(sb + lds_byte2(wc * 64 + n * 16 + fr, ks * 32 + fq * 8));
; #pragma unroll
;       for (int m = 1; m < 8; ++m) At[m] = *(const bf16x8*)(sa + lds_byte2(wr * 128 + m * 16 + fr, ks * 32 + fq * 8));
;       {
;         __builtin_amdgcn_sched_barrier(0);
;         if (t + 1 < nt) { G8_STAGE_R(cur ^ 1, Ab + (t + 1) * 64, Bb + (t + 1) * 64, 2 * ks, 2 * ks + 2); }
;         else if (has_next) { G8_STAGE_R(0, Abn, Bbn, 2 * ks, 2 * ks + 2); }
;         __builtin_amdgcn_sched_barrier(0);
;       }
; #pragma unroll
;       for (int m = 0; m < 8; ++m)
; #pragma unroll
;         for (int n = 0; n < 4; ++n) acc[m][n] = MFMA16(At[m], Bf[n], acc[m][n]);
.LBB0_1694:
	s_lshl_b32 s0, s79, 3
	s_add_i32 s0, s28, s0
	s_add_i32 s0, s0, s81
	s_lshl_b32 s1, s78, 3
	s_sub_i32 s0, s0, s1
	s_lshl_b32 s1, s0, 8
	s_mul_i32 s0, s0, 0x168000
	s_mul_hi_i32 s1, s1, 0x1680
	s_add_u32 s0, s91, s0
	v_lshlrev_b64 v[178:179], 1, v[4:5]
	s_addc_u32 s1, s72, s1
	v_lshlrev_b64 v[180:181], 1, v[2:3]
	v_lshlrev_b64 v[194:195], 1, v[6:7]
	v_lshlrev_b64 v[196:197], 1, v[0:1]
	v_and_b32_e32 v198, 15, v8
	v_lshl_add_u64 v[130:131], s[0:1], 0, v[178:179]
	v_lshl_add_u64 v[132:133], s[0:1], 0, v[180:181]
	v_lshl_add_u64 v[134:135], s[0:1], 0, v[194:195]
	v_lshl_add_u64 v[136:137], s[0:1], 0, v[196:197]
	v_readlane_b32 s0, v253, 25
	v_and_b32_e32 v206, 63, v8
	v_ashrrev_i32_e32 v10, 8, v8
	v_and_b32_e32 v204, 3, v9
	v_and_b32_e32 v9, 48, v8
	v_lshlrev_b32_e32 v199, 2, v198
	v_lshlrev_b32_e32 v8, 6, v8
	s_add_u32 s0, s0, s84
	v_readlane_b32 s1, v253, 26
	v_lshlrev_b32_e32 v11, 6, v198
	v_and_b32_e32 v12, 32, v199
	v_lshlrev_b32_e32 v156, 14, v10
	v_and_b32_e32 v8, 0x3c0, v8
	s_addc_u32 s1, s1, s85
	v_lshlrev_b32_e32 v153, 13, v204
	v_bitop3_b32 v155, v11, v12, v9 bitop3:0x36
	v_lshlrev_b32_e32 v205, 7, v10
	v_or_b32_e32 v150, 0x800, v156
	v_bitop3_b32 v154, v8, v12, v9 bitop3:0x36
	v_or_b32_e32 v152, 0x1000, v156
	v_or_b32_e32 v151, 0x1800, v156
	v_or_b32_e32 v149, 0x2000, v156
	v_or_b32_e32 v148, 0x2800, v156
	v_or_b32_e32 v147, 0x3000, v156
	v_or_b32_e32 v146, 0x3800, v156
	v_lshl_add_u64 v[138:139], s[0:1], 0, v[178:179]
	v_lshl_add_u64 v[140:141], s[0:1], 0, v[180:181]
	v_lshl_add_u64 v[142:143], s[0:1], 0, v[194:195]
	v_lshl_add_u64 v[144:145], s[0:1], 0, v[196:197]
	s_mov_b64 s[0:1], 0
	s_mov_b32 s58, 0
	s_waitcnt vmcnt(8)
	s_mov_b32 s70, 0
	v_add3_u32 v0, s70, v155, v153
	v_add3_u32 v157, s70, v155, v156
	v_add3_u32 v238, s70, v154, v152
	v_add3_u32 v240, s70, v154, v149
	v_add3_u32 v242, s70, v154, v147
	v_add3_u32 v207, s70, v154, v150
	v_add3_u32 v239, s70, v154, v151
	v_add3_u32 v241, s70, v154, v148
	v_add3_u32 v243, s70, v154, v146
	ds_read_b128 v[158:161], v0 offset:32768
	ds_read_b128 v[162:165], v0 offset:34816
	ds_read_b128 v[174:177], v157
	ds_read_b128 v[186:189], v207
	ds_read_b128 v[190:193], v238
	ds_read_b128 v[212:215], v239
	ds_read_b128 v[222:225], v240
	ds_read_b128 v[226:229], v241
	ds_read_b128 v[230:233], v242
	ds_read_b128 v[234:237], v243
	ds_read_b128 v[166:169], v0 offset:36864
	ds_read_b128 v[170:173], v0 offset:38912
	s_and_b32 s59, s58, 0x10000
	s_xor_b32 s70, s59, 0x10000
	v_add_u32_e32 v244, s70, v185
	s_nop 0
	v_readfirstlane_b32 s59, v244
	s_waitcnt lgkmcnt(8)
	v_mfma_f32_16x16x32_bf16 v[126:129], v[174:177], v[158:161], 0
	v_mfma_f32_16x16x32_bf16 v[122:125], v[174:177], v[162:165], 0
	s_mov_b32 m0, s59
	v_lshl_add_u64 v[208:209], v[130:131], 0, s[0:1]
	global_load_lds_dwordx4 v[208:209], off
	v_mfma_f32_16x16x32_bf16 v[110:113], v[186:189], v[158:161], 0
	v_mfma_f32_16x16x32_bf16 v[106:109], v[186:189], v[162:165], 0
	s_add_u32 m0, s59, 0x8000
	v_lshl_add_u64 v[208:209], v[138:139], 0, s[0:1]
	global_load_lds_dwordx4 v[208:209], off
	s_waitcnt lgkmcnt(6)
	v_mfma_f32_16x16x32_bf16 v[94:97], v[190:193], v[158:161], 0
	v_mfma_f32_16x16x32_bf16 v[90:93], v[190:193], v[162:165], 0
	s_add_u32 m0, s59, 0x2000
	v_lshl_add_u64 v[208:209], v[132:133], 0, s[0:1]
	global_load_lds_dwordx4 v[208:209], off
	v_mfma_f32_16x16x32_bf16 v[78:81], v[212:215], v[158:161], 0
	v_mfma_f32_16x16x32_bf16 v[74:77], v[212:215], v[162:165], 0
	s_add_u32 m0, s59, 0xa000
	v_lshl_add_u64 v[208:209], v[140:141], 0, s[0:1]
	global_load_lds_dwordx4 v[208:209], off
	s_waitcnt lgkmcnt(4)
	v_mfma_f32_16x16x32_bf16 v[62:65], v[222:225], v[158:161], 0
	v_mfma_f32_16x16x32_bf16 v[58:61], v[222:225], v[162:165], 0
	s_add_u32 m0, s59, 0x4000
	v_lshl_add_u64 v[208:209], v[134:135], 0, s[0:1]
	global_load_lds_dwordx4 v[208:209], off
	v_mfma_f32_16x16x32_bf16 v[46:49], v[226:229], v[158:161], 0
	v_mfma_f32_16x16x32_bf16 v[42:45], v[226:229], v[162:165], 0
	s_add_u32 m0, s59, 0xc000
	v_lshl_add_u64 v[208:209], v[142:143], 0, s[0:1]
	global_load_lds_dwordx4 v[208:209], off
	s_waitcnt lgkmcnt(2)
	v_mfma_f32_16x16x32_bf16 v[30:33], v[230:233], v[158:161], 0
	v_mfma_f32_16x16x32_bf16 v[26:29], v[230:233], v[162:165], 0
	s_add_u32 m0, s59, 0x6000
	v_lshl_add_u64 v[208:209], v[136:137], 0, s[0:1]
	global_load_lds_dwordx4 v[208:209], off
	v_mfma_f32_16x16x32_bf16 v[14:17], v[234:237], v[158:161], 0
	v_mfma_f32_16x16x32_bf16 v[10:13], v[234:237], v[162:165], 0
	s_add_u32 m0, s59, 0xe000
	v_lshl_add_u64 v[208:209], v[144:145], 0, s[0:1]
	global_load_lds_dwordx4 v[208:209], off
	ds_read_b128 v[158:161], v0 offset:33792
	ds_read_b128 v[162:165], v0 offset:35840
	s_waitcnt lgkmcnt(2)
; #define MFMA16(a, b, c) __builtin_amdgcn_mfma_f32_16x16x32_bf16((a), (b), (c), 0, 0, 0)
; template <class Epi>
; DI void gemm8_tile(const bf16_t* __restrict__ Ab, int lda, const bf16_t* __restrict__ Bb, int ldb, int K, int brow, int bcol, const Epi epi,
;                    bool staged, bool has_next, const bf16_t* __restrict__ Abn, const bf16_t* __restrict__ Bbn) {
;     ...
; #pragma unroll
;     for (int ks = 0; ks < 2; ++ks) {
;       bf16x8 At[8], Bf[4];
;       Bf[0] = *(const bf16x8*)(sb + lds_byte2(wc * 64 + fr, ks * 32 + fq * 8));
;       At[0] = *(const bf16x8*)(sa + lds_byte2(wr * 128 + fr, ks * 32 + fq * 8));
; #pragma unroll
;       for (int n = 1; n < 4; ++n) Bf[n] = *(const bf16x8*)(sb + lds_byte2(wc * 64 + n * 16 + fr, ks * 32 + fq * 8));
; #pragma unroll
;       for (int m = 1; m < 8; ++m) At[m] = *(const bf16x8*)(sa + lds_byte2(wr * 128 + m * 16 + fr, ks * 32 + fq * 8));
;       {
;         __builtin_amdgcn_sched_barrier(0);
;         if (t + 1 < nt) { G8_STAGE_R(cur ^ 1, Ab + (t + 1) * 64, Bb + (t + 1) * 64, 2 * ks, 2 * ks + 2); }
;         else if (has_next) { G8_STAGE_R(0, Abn, Bbn, 2 * ks, 2 * ks + 2); }
;         __builtin_amdgcn_sched_barrier(0);
;       }
; #pragma unroll
;       for (int m = 0; m < 8; ++m)
; #pragma unroll
;         for (int n = 0; n < 4; ++n) acc[m][n] = MFMA16(At[m], Bf[n], acc[m][n]);
;       __builtin_amdgcn_sched_barrier(0);
;     }
;     asm volatile("s_waitcnt vmcnt(0)" ::: "memory");
;     __syncthreads();
	v_mfma_f32_16x16x32_bf16 v[118:121], v[174:177], v[166:169], 0
	v_mfma_f32_16x16x32_bf16 v[114:117], v[174:177], v[170:173], 0
	ds_read_b128 v[174:177], v157 offset:1024
	v_mfma_f32_16x16x32_bf16 v[102:105], v[186:189], v[166:169], 0
	v_mfma_f32_16x16x32_bf16 v[98:101], v[186:189], v[170:173], 0
	ds_read_b128 v[186:189], v207 offset:1024
	v_mfma_f32_16x16x32_bf16 v[86:89], v[190:193], v[166:169], 0
	v_mfma_f32_16x16x32_bf16 v[82:85], v[190:193], v[170:173], 0
	ds_read_b128 v[190:193], v238 offset:1024
	v_mfma_f32_16x16x32_bf16 v[70:73], v[212:215], v[166:169], 0
	v_mfma_f32_16x16x32_bf16 v[66:69], v[212:215], v[170:173], 0
	ds_read_b128 v[212:215], v239 offset:1024
	v_mfma_f32_16x16x32_bf16 v[54:57], v[222:225], v[166:169], 0
	v_mfma_f32_16x16x32_bf16 v[50:53], v[222:225], v[170:173], 0
	ds_read_b128 v[222:225], v240 offset:1024
	v_mfma_f32_16x16x32_bf16 v[38:41], v[226:229], v[166:169], 0
	v_mfma_f32_16x16x32_bf16 v[34:37], v[226:229], v[170:173], 0
	ds_read_b128 v[226:229], v241 offset:1024
	v_mfma_f32_16x16x32_bf16 v[22:25], v[230:233], v[166:169], 0
	v_mfma_f32_16x16x32_bf16 v[18:21], v[230:233], v[170:173], 0
	ds_read_b128 v[230:233], v242 offset:1024
	v_mfma_f32_16x16x32_bf16 v[6:9], v[234:237], v[166:169], 0
	v_mfma_f32_16x16x32_bf16 v[2:5], v[234:237], v[170:173], 0
	ds_read_b128 v[234:237], v243 offset:1024
	ds_read_b128 v[166:169], v0 offset:37888
	ds_read_b128 v[170:173], v0 offset:39936
	s_waitcnt lgkmcnt(8)
	v_mfma_f32_16x16x32_bf16 v[126:129], v[174:177], v[158:161], v[126:129]
	v_mfma_f32_16x16x32_bf16 v[122:125], v[174:177], v[162:165], v[122:125]
	v_add3_u32 v0, s70, v155, v153
	v_mfma_f32_16x16x32_bf16 v[110:113], v[186:189], v[158:161], v[110:113]
	v_mfma_f32_16x16x32_bf16 v[106:109], v[186:189], v[162:165], v[106:109]
	v_add3_u32 v157, s70, v155, v156
	s_waitcnt lgkmcnt(6)
	v_mfma_f32_16x16x32_bf16 v[94:97], v[190:193], v[158:161], v[94:97]
	v_mfma_f32_16x16x32_bf16 v[90:93], v[190:193], v[162:165], v[90:93]
	v_add3_u32 v238, s70, v154, v152
	v_mfma_f32_16x16x32_bf16 v[78:81], v[212:215], v[158:161], v[78:81]
	v_mfma_f32_16x16x32_bf16 v[74:77], v[212:215], v[162:165], v[74:77]
	v_add3_u32 v240, s70, v154, v149
	s_waitcnt lgkmcnt(4)
	v_mfma_f32_16x16x32_bf16 v[62:65], v[222:225], v[158:161], v[62:65]
	v_mfma_f32_16x16x32_bf16 v[58:61], v[222:225], v[162:165], v[58:61]
	v_add3_u32 v242, s70, v154, v147
	v_mfma_f32_16x16x32_bf16 v[46:49], v[226:229], v[158:161], v[46:49]
	v_mfma_f32_16x16x32_bf16 v[42:45], v[226:229], v[162:165], v[42:45]
	v_add3_u32 v207, s70, v154, v150
	s_waitcnt lgkmcnt(2)
	v_mfma_f32_16x16x32_bf16 v[30:33], v[230:233], v[158:161], v[30:33]
	v_mfma_f32_16x16x32_bf16 v[26:29], v[230:233], v[162:165], v[26:29]
	v_add3_u32 v239, s70, v154, v151
	v_mfma_f32_16x16x32_bf16 v[14:17], v[234:237], v[158:161], v[14:17]
	v_mfma_f32_16x16x32_bf16 v[10:13], v[234:237], v[162:165], v[10:13]
	v_add3_u32 v241, s70, v154, v148
	v_add3_u32 v243, s70, v154, v146
	s_waitcnt vmcnt(0) lgkmcnt(0)
	s_barrier
	ds_read_b128 v[158:161], v0 offset:32768
	ds_read_b128 v[162:165], v0 offset:34816
	v_mfma_f32_16x16x32_bf16 v[118:121], v[174:177], v[166:169], v[118:121]
	v_mfma_f32_16x16x32_bf16 v[114:117], v[174:177], v[170:173], v[114:117]
	ds_read_b128 v[174:177], v157
	v_mfma_f32_16x16x32_bf16 v[102:105], v[186:189], v[166:169], v[102:105]
	v_mfma_f32_16x16x32_bf16 v[98:101], v[186:189], v[170:173], v[98:101]
	ds_read_b128 v[186:189], v207
	v_mfma_f32_16x16x32_bf16 v[86:89], v[190:193], v[166:169], v[86:89]
	v_mfma_f32_16x16x32_bf16 v[82:85], v[190:193], v[170:173], v[82:85]
	ds_read_b128 v[190:193], v238
	v_mfma_f32_16x16x32_bf16 v[70:73], v[212:215], v[166:169], v[70:73]
	v_mfma_f32_16x16x32_bf16 v[66:69], v[212:215], v[170:173], v[66:69]
	ds_read_b128 v[212:215], v239
	v_mfma_f32_16x16x32_bf16 v[54:57], v[222:225], v[166:169], v[54:57]
	v_mfma_f32_16x16x32_bf16 v[50:53], v[222:225], v[170:173], v[50:53]
	ds_read_b128 v[222:225], v240
	v_mfma_f32_16x16x32_bf16 v[38:41], v[226:229], v[166:169], v[38:41]
	v_mfma_f32_16x16x32_bf16 v[34:37], v[226:229], v[170:173], v[34:37]
	ds_read_b128 v[226:229], v241
	v_mfma_f32_16x16x32_bf16 v[22:25], v[230:233], v[166:169], v[22:25]
	v_mfma_f32_16x16x32_bf16 v[18:21], v[230:233], v[170:173], v[18:21]
	ds_read_b128 v[230:233], v242
	v_mfma_f32_16x16x32_bf16 v[6:9], v[234:237], v[166:169], v[6:9]
	v_mfma_f32_16x16x32_bf16 v[2:5], v[234:237], v[170:173], v[2:5]
	ds_read_b128 v[234:237], v243
	ds_read_b128 v[166:169], v0 offset:36864
	ds_read_b128 v[170:173], v0 offset:38912
	s_add_u32 s0, s0, 0x80
	s_addc_u32 s1, s1, 0
	s_add_i32 s58, s58, 0x10000
